# row phases: wave all-reduce via DPP adds + permlane16/32 swaps instead of 6 dependent ds_bpermute round trips (10 fast-path sites)
# baseline (speedup 1.0000x reference)
.LBB0_114:
	s_or_b64 exec, exec, s[4:5]
	v_add_u32_e32 v12, 0x6000, v130
	v_ashrrev_i32_e32 v12, 12, v12
	s_movk_i32 s0, 0x1fff
	v_add_u32_e32 v12, 1, v12
	v_cmp_lt_i32_e32 vcc, s0, v152
	s_waitcnt vmcnt(13)
	v_lshlrev_b32_e32 v74, 16, v0
	v_and_b32_e32 v75, 0xffff0000, v0
	v_cndmask_b32_e32 v0, 0, v12, vcc
	v_lshlrev_b32_e32 v80, 16, v1
	v_and_b32_e32 v81, 0xffff0000, v1
	v_mul_hi_i32_i24_e32 v1, 0x2400, v0
	v_mul_i32_i24_e32 v0, 0x2400, v0
	v_lshlrev_b64 v[0:1], 2, v[0:1]
	s_waitcnt vmcnt(9)
	v_lshlrev_b32_e32 v72, 16, v2
	v_and_b32_e32 v73, 0xffff0000, v2
	v_lshlrev_b32_e32 v76, 16, v3
	v_and_b32_e32 v77, 0xffff0000, v3
	v_lshl_add_u64 v[2:3], v[40:41], 0, v[0:1]
	v_lshlrev_b32_e32 v92, 16, v8
	v_and_b32_e32 v93, 0xffff0000, v8
	v_lshlrev_b32_e32 v94, 16, v9
	v_and_b32_e32 v95, 0xffff0000, v9
	v_lshlrev_b32_e32 v86, 16, v10
	v_and_b32_e32 v87, 0xffff0000, v10
	v_lshlrev_b32_e32 v90, 16, v11
	v_and_b32_e32 v91, 0xffff0000, v11
	v_lshlrev_b32_e32 v82, 16, v4
	v_and_b32_e32 v83, 0xffff0000, v4
	v_lshlrev_b32_e32 v88, 16, v5
	v_and_b32_e32 v89, 0xffff0000, v5
	v_lshlrev_b32_e32 v78, 16, v6
	v_and_b32_e32 v79, 0xffff0000, v6
	v_lshlrev_b32_e32 v84, 16, v7
	v_and_b32_e32 v85, 0xffff0000, v7
	global_load_dwordx4 v[4:7], v[2:3], off
	global_load_dwordx4 v[8:11], v[2:3], off offset:1024
	global_load_dwordx4 v[20:23], v[42:43], off
	global_load_dwordx4 v[12:15], v[42:43], off offset:1024
	global_load_dwordx4 v[16:19], v[2:3], off offset:2048
	global_load_dwordx4 v[24:27], v[2:3], off offset:3072
	global_load_dwordx4 v[32:35], v[42:43], off offset:2048
	global_load_dwordx4 v[28:31], v[42:43], off offset:3072
	v_lshl_add_u64 v[0:1], s[24:25], 0, v[0:1]
	v_mov_b32_e32 v55, v131
	v_lshl_add_u64 v[64:65], v[0:1], 0, v[54:55]
	s_movk_i32 s0, 0x1000
	v_add_co_u32_e32 v0, vcc, s0, v64
	s_waitcnt vmcnt(15)
	v_lshlrev_b32_e32 v142, 16, v112
	v_addc_co_u32_e32 v1, vcc, 0, v65, vcc
	global_load_dwordx4 v[0:3], v[0:1], off
	v_and_b32_e32 v143, 0xffff0000, v112
	s_waitcnt vmcnt(15)
	v_lshlrev_b32_e32 v144, 16, v120
	v_and_b32_e32 v145, 0xffff0000, v120
	v_lshlrev_b32_e32 v112, 16, v113
	v_and_b32_e32 v113, 0xffff0000, v113
	v_lshlrev_b32_e32 v120, 16, v121
	v_and_b32_e32 v121, 0xffff0000, v121
	v_pk_add_f32 v[142:143], v[142:143], v[144:145]
	v_pk_add_f32 v[112:113], v[112:113], v[120:121]
	v_lshlrev_b32_e32 v120, 16, v96
	v_and_b32_e32 v121, 0xffff0000, v96
	v_lshlrev_b32_e32 v144, 16, v98
	v_and_b32_e32 v145, 0xffff0000, v98
	v_lshlrev_b32_e32 v96, 16, v97
	v_and_b32_e32 v97, 0xffff0000, v97
	v_lshlrev_b32_e32 v98, 16, v99
	v_and_b32_e32 v99, 0xffff0000, v99
	v_pk_add_f32 v[120:121], v[120:121], v[144:145]
	v_pk_add_f32 v[96:97], v[96:97], v[98:99]
	v_mov_b32_e32 v144, v143
	v_mov_b32_e32 v145, v113
	v_mov_b32_e32 v98, v142
	v_mov_b32_e32 v99, v112
	v_pk_mul_f32 v[144:145], v[144:145], v[144:145]
	v_mov_b32_e32 v154, v121
	v_mov_b32_e32 v155, v97
	v_pk_fma_f32 v[98:99], v[98:99], v[98:99], v[144:145]
	v_mov_b32_e32 v144, v120
	v_mov_b32_e32 v145, v96
	v_pk_mul_f32 v[154:155], v[154:155], v[154:155]
	s_waitcnt vmcnt(13)
	v_lshlrev_b32_e32 v156, 16, v124
	v_pk_fma_f32 v[144:145], v[144:145], v[144:145], v[154:155]
	v_and_b32_e32 v157, 0xffff0000, v124
	v_pk_add_f32 v[154:155], v[144:145], v[144:145] op_sel:[0,1] op_sel_hi:[1,0]
	v_lshlrev_b32_e32 v144, 16, v116
	v_and_b32_e32 v145, 0xffff0000, v116
	v_lshlrev_b32_e32 v116, 16, v117
	v_and_b32_e32 v117, 0xffff0000, v117
	v_lshlrev_b32_e32 v124, 16, v125
	v_and_b32_e32 v125, 0xffff0000, v125
	v_pk_add_f32 v[144:145], v[144:145], v[156:157]
	v_pk_add_f32 v[116:117], v[116:117], v[124:125]
	v_lshlrev_b32_e32 v124, 16, v108
	v_and_b32_e32 v125, 0xffff0000, v108
	v_lshlrev_b32_e32 v156, 16, v104
	v_and_b32_e32 v157, 0xffff0000, v104
	v_lshlrev_b32_e32 v108, 16, v109
	v_and_b32_e32 v109, 0xffff0000, v109
	v_lshlrev_b32_e32 v104, 16, v105
	v_and_b32_e32 v105, 0xffff0000, v105
	v_pk_add_f32 v[124:125], v[124:125], v[156:157]
	v_pk_add_f32 v[104:105], v[108:109], v[104:105]
	v_mov_b32_e32 v156, v145
	v_mov_b32_e32 v157, v117
	v_mov_b32_e32 v108, v144
	v_mov_b32_e32 v109, v116
	v_pk_mul_f32 v[156:157], v[156:157], v[156:157]
	v_mov_b32_e32 v182, v125
	v_mov_b32_e32 v183, v105
	v_pk_fma_f32 v[108:109], v[108:109], v[108:109], v[156:157]
	v_mov_b32_e32 v156, v124
	v_mov_b32_e32 v157, v104
	v_pk_mul_f32 v[182:183], v[182:183], v[182:183]
	s_waitcnt vmcnt(11)
	v_lshlrev_b32_e32 v184, 16, v122
	v_pk_fma_f32 v[156:157], v[156:157], v[156:157], v[182:183]
	v_lshlrev_b32_e32 v182, 16, v114
	v_and_b32_e32 v183, 0xffff0000, v114
	v_and_b32_e32 v185, 0xffff0000, v122
	v_pk_add_f32 v[182:183], v[182:183], v[184:185]
	v_lshlrev_b32_e32 v114, 16, v115
	v_and_b32_e32 v115, 0xffff0000, v115
	v_lshlrev_b32_e32 v122, 16, v123
	v_and_b32_e32 v123, 0xffff0000, v123
	v_lshlrev_b32_e32 v70, 16, v68
	v_and_b32_e32 v71, 0xffff0000, v68
	v_pk_add_f32 v[114:115], v[114:115], v[122:123]
	v_lshlrev_b32_e32 v122, 16, v102
	v_and_b32_e32 v123, 0xffff0000, v102
	v_lshlrev_b32_e32 v184, 16, v100
	v_and_b32_e32 v185, 0xffff0000, v100
	v_lshlrev_b32_e32 v102, 16, v103
	v_and_b32_e32 v103, 0xffff0000, v103
	v_lshlrev_b32_e32 v100, 16, v101
	v_and_b32_e32 v101, 0xffff0000, v101
	v_mul_f32_e32 v68, v183, v183
	s_waitcnt vmcnt(10)
	v_lshlrev_b32_e32 v190, 16, v118
	v_and_b32_e32 v191, 0xffff0000, v118
	s_waitcnt vmcnt(9)
	v_lshlrev_b32_e32 v192, 16, v126
	v_and_b32_e32 v193, 0xffff0000, v126
	v_lshlrev_b32_e32 v118, 16, v119
	v_and_b32_e32 v119, 0xffff0000, v119
	v_lshlrev_b32_e32 v126, 16, v127
	v_and_b32_e32 v127, 0xffff0000, v127
	v_pk_add_f32 v[100:101], v[102:103], v[100:101]
	v_pk_fma_f32 v[102:103], v[182:183], v[182:183], v[68:69] op_sel_hi:[1,1,0]
	v_mul_f32_e32 v68, v115, v115
	v_pk_add_f32 v[190:191], v[190:191], v[192:193]
	v_pk_add_f32 v[118:119], v[118:119], v[126:127]
	v_lshlrev_b32_e32 v126, 16, v110
	v_and_b32_e32 v127, 0xffff0000, v110
	v_lshlrev_b32_e32 v192, 16, v106
	v_and_b32_e32 v193, 0xffff0000, v106
	v_lshlrev_b32_e32 v110, 16, v111
	v_and_b32_e32 v111, 0xffff0000, v111
	v_lshlrev_b32_e32 v106, 16, v107
	v_and_b32_e32 v107, 0xffff0000, v107
	v_pk_add_f32 v[98:99], v[98:99], v[98:99] op_sel:[0,1] op_sel_hi:[1,0]
	v_pk_add_f32 v[108:109], v[108:109], v[108:109] op_sel:[0,1] op_sel_hi:[1,0]
	v_pk_add_f32 v[122:123], v[122:123], v[184:185]
	v_pk_fma_f32 v[184:185], v[114:115], v[114:115], v[68:69] op_sel_hi:[1,1,0]
	v_pk_add_f32 v[126:127], v[126:127], v[192:193]
	v_pk_add_f32 v[106:107], v[110:111], v[106:107]
	v_pk_mul_f32 v[110:111], v[190:191], v[190:191]
	v_pk_mul_f32 v[192:193], v[118:119], v[118:119]
	v_mul_f32_e32 v68, v123, v123
	v_mov_b32_e32 v99, v110
	v_mov_b32_e32 v109, v111
	v_mov_b32_e32 v103, v192
	v_mov_b32_e32 v185, v193
	v_pk_fma_f32 v[186:187], v[122:123], v[122:123], v[68:69] op_sel_hi:[1,1,0]
	v_mul_f32_e32 v68, v101, v101
	v_pk_add_f32 v[98:99], v[98:99], v[108:109]
	v_pk_add_f32 v[102:103], v[102:103], v[184:185]
	v_pk_add_f32 v[156:157], v[156:157], v[156:157] op_sel:[0,1] op_sel_hi:[1,0]
	v_pk_fma_f32 v[188:189], v[100:101], v[100:101], v[68:69] op_sel_hi:[1,1,0]
	v_pk_add_f32 v[98:99], v[98:99], v[102:103]
	v_pk_mul_f32 v[102:103], v[126:127], v[126:127]
	v_pk_mul_f32 v[108:109], v[106:107], v[106:107]
	v_mov_b32_e32 v155, v102
	v_mov_b32_e32 v157, v103
	v_mov_b32_e32 v187, v108
	v_mov_b32_e32 v189, v109
	v_pk_add_f32 v[102:103], v[154:155], v[156:157]
	v_pk_add_f32 v[108:109], v[186:187], v[188:189]
	s_waitcnt vmcnt(6)
	v_pk_mul_f32 v[154:155], v[4:5], v[20:21]
	v_pk_add_f32 v[102:103], v[102:103], v[108:109]
	v_mov_b32_e32 v109, v98
	v_mov_b32_e32 v108, v102
	v_mov_b32_e32 v98, v103
	v_pk_add_f32 v[98:99], v[108:109], v[98:99]
	v_mov_b32_e32 v240, v98
	v_mov_b32_e32 v241, v99
	s_nop 1
	v_add_f32_dpp v240, v240, v240 quad_perm:[1,0,3,2] row_mask:0xf bank_mask:0xf
	v_add_f32_dpp v241, v241, v241 quad_perm:[1,0,3,2] row_mask:0xf bank_mask:0xf
	s_nop 0
	v_add_f32_dpp v240, v240, v240 quad_perm:[2,3,0,1] row_mask:0xf bank_mask:0xf
	v_add_f32_dpp v241, v241, v241 quad_perm:[2,3,0,1] row_mask:0xf bank_mask:0xf
	s_nop 0
	v_add_f32_dpp v240, v240, v240 row_half_mirror row_mask:0xf bank_mask:0xf
	v_add_f32_dpp v241, v241, v241 row_half_mirror row_mask:0xf bank_mask:0xf
	s_nop 0
	v_add_f32_dpp v240, v240, v240 row_mirror row_mask:0xf bank_mask:0xf
	v_add_f32_dpp v241, v241, v241 row_mirror row_mask:0xf bank_mask:0xf
	v_mov_b32_e32 v242, v240
	v_mov_b32_e32 v243, v241
	s_nop 1
	v_permlane16_swap_b32_e32 v240, v242
	v_permlane16_swap_b32_e32 v241, v243
	v_add_f32_e32 v240, v240, v242
	v_add_f32_e32 v241, v241, v243
	v_mov_b32_e32 v242, v240
	v_mov_b32_e32 v243, v241
	s_nop 1
	v_permlane32_swap_b32_e32 v240, v242
	v_permlane32_swap_b32_e32 v241, v243
	v_add_f32_e32 v240, v240, v242
	v_add_f32_e32 v241, v241, v243
	v_pk_mul_f32 v[110:111], v[6:7], v[22:23]
	s_waitcnt vmcnt(5)
	v_pk_mul_f32 v[156:157], v[8:9], v[12:13]
	s_waitcnt vmcnt(2)
	v_pk_mul_f32 v[186:187], v[16:17], v[32:33]
	s_mov_b64 s[0:1], 0x1000
	v_lshl_add_u64 v[12:13], v[64:65], 0, s[0:1]
	v_pk_mul_f32 v[184:185], v[18:19], v[34:35]
	s_waitcnt vmcnt(1)
	v_pk_mul_f32 v[188:189], v[26:27], v[30:31]
	v_pk_mul_f32 v[192:193], v[24:25], v[28:29]
	v_pk_mul_f32 v[102:103], v[10:11], v[14:15]
	s_mov_b32 s0, 0x358637bd
	s_mov_b32 s6, 0x3a800000
	v_lshlrev_b32_e32 v108, 16, v66
	global_load_dwordx4 v[4:7], v[64:65], off
	v_and_b32_e32 v109, 0xffff0000, v66
	v_lshlrev_b32_e32 v68, 16, v69
	v_and_b32_e32 v69, 0xffff0000, v69
	global_load_dwordx4 v[8:11], v[12:13], off offset:3072
	global_load_dwordx4 v[32:35], v[44:45], off
	global_load_dwordx4 v[20:23], v[44:45], off offset:1024
	s_waitcnt vmcnt(4)
	v_pk_add_f32 v[98:99], v[2:3], 1.0 op_sel_hi:[1,0]
	v_lshlrev_b32_e32 v66, 16, v67
	global_load_dwordx4 v[28:31], v[12:13], off offset:1024
	global_load_dwordx4 v[24:27], v[12:13], off offset:2048
	global_load_dwordx4 v[16:19], v[44:45], off offset:2048
	s_nop 0
	global_load_dwordx4 v[12:15], v[44:45], off offset:3072
	v_and_b32_e32 v67, 0xffff0000, v67
	v_pk_add_f32 v[0:1], v[0:1], 1.0 op_sel_hi:[1,0]
	v_add_u32_e32 v130, 0x1000, v130
	v_mov_b32_e32 v194, v240
	v_mov_b32_e32 v195, v241
	v_mov_b64_e32 v[2:3], s[0:1]
	v_pk_fma_f32 v[194:195], v[194:195], s[6:7], v[2:3] op_sel_hi:[1,0,0]
	s_mov_b32 s0, 0x800000
	v_mul_f32_e32 v55, 0x4b800000, v195
	v_cmp_gt_f32_e32 vcc, s0, v195
	v_mul_f32_e32 v153, 0x4b800000, v194
	v_cmp_gt_f32_e64 s[4:5], s0, v194
	v_cndmask_b32_e32 v55, v195, v55, vcc
	v_rsq_f32_e32 v55, v55
	v_cndmask_b32_e64 v153, v194, v153, s[4:5]
	v_rsq_f32_e32 v153, v153
	v_mul_f32_e32 v170, 0x45800000, v55
	v_cndmask_b32_e32 v55, v55, v170, vcc
	v_mul_f32_e32 v194, 0.5, v55
	v_mul_f32_e32 v55, 0x45800000, v153
	v_cndmask_b32_e64 v55, v153, v55, s[4:5]
	v_mul_f32_e32 v196, 0.5, v55
	v_pk_mul_f32 v[96:97], v[96:97], v[196:197] op_sel_hi:[1,0]
	v_pk_mul_f32 v[142:143], v[142:143], v[194:195] op_sel_hi:[1,0]
	v_pk_fma_f32 v[90:91], v[110:111], v[96:97], v[90:91]
	v_pk_mul_f32 v[96:97], v[144:145], v[194:195] op_sel_hi:[1,0]
	v_pk_mul_f32 v[112:113], v[112:113], v[194:195] op_sel_hi:[1,0]
	v_pk_fma_f32 v[82:83], v[156:157], v[96:97], v[82:83]
	v_pk_mul_f32 v[96:97], v[124:125], v[196:197] op_sel_hi:[1,0]
	v_pk_fma_f32 v[94:95], v[110:111], v[112:113], v[94:95]
	v_pk_fma_f32 v[78:79], v[156:157], v[96:97], v[78:79]
	v_pk_mul_f32 v[96:97], v[182:183], v[194:195] op_sel_hi:[1,0]
	v_pk_fma_f32 v[92:93], v[154:155], v[142:143], v[92:93]
	v_pk_fma_f32 v[74:75], v[186:187], v[96:97], v[74:75]
	v_pk_mul_f32 v[96:97], v[122:123], v[196:197] op_sel_hi:[1,0]
	v_pk_mul_f32 v[112:113], v[120:121], v[196:197] op_sel_hi:[1,0]
	v_pk_fma_f32 v[72:73], v[186:187], v[96:97], v[72:73]
	v_pk_mul_f32 v[96:97], v[190:191], v[194:195] op_sel_hi:[1,0]
	v_pk_mul_f32 v[100:101], v[100:101], v[196:197] op_sel_hi:[1,0]
	v_pk_fma_f32 v[70:71], v[192:193], v[96:97], v[70:71]
	v_pk_mul_f32 v[96:97], v[126:127], v[196:197] op_sel_hi:[1,0]
	v_pk_fma_f32 v[86:87], v[154:155], v[112:113], v[86:87]
	v_pk_mul_f32 v[110:111], v[116:117], v[194:195] op_sel_hi:[1,0]
	v_pk_mul_f32 v[104:105], v[104:105], v[196:197] op_sel_hi:[1,0]
	v_pk_fma_f32 v[76:77], v[184:185], v[100:101], v[76:77]
	v_pk_mul_f32 v[100:101], v[118:119], v[194:195] op_sel_hi:[1,0]
	v_pk_fma_f32 v[96:97], v[192:193], v[96:97], v[108:109]
	v_cvt_pk_bf16_f32 v92, v92, v93
	v_cvt_pk_bf16_f32 v93, v94, v95
	v_pk_fma_f32 v[88:89], v[102:103], v[110:111], v[88:89]
	v_pk_fma_f32 v[84:85], v[102:103], v[104:105], v[84:85]
	v_pk_mul_f32 v[102:103], v[114:115], v[194:195] op_sel_hi:[1,0]
	v_pk_fma_f32 v[68:69], v[188:189], v[100:101], v[68:69]
	v_pk_mul_f32 v[100:101], v[106:107], v[196:197] op_sel_hi:[1,0]
	v_cvt_pk_bf16_f32 v86, v86, v87
	v_cvt_pk_bf16_f32 v87, v90, v91
	v_cvt_pk_bf16_f32 v90, v96, v97
	v_and_b32_e32 v97, 0xffff0000, v93
	v_and_b32_e32 v96, 0xffff0000, v92
	v_pk_fma_f32 v[80:81], v[184:185], v[102:103], v[80:81]
	v_pk_fma_f32 v[66:67], v[188:189], v[100:101], v[66:67]
	v_cvt_pk_bf16_f32 v82, v82, v83
	v_cvt_pk_bf16_f32 v83, v88, v89
	v_lshlrev_b32_e32 v95, 16, v93
	v_lshlrev_b32_e32 v94, 16, v92
	v_pk_mul_f32 v[100:101], v[96:97], v[96:97]
	v_cvt_pk_bf16_f32 v78, v78, v79
	v_cvt_pk_bf16_f32 v79, v84, v85
	v_cvt_pk_bf16_f32 v84, v74, v75
	v_cvt_pk_bf16_f32 v85, v80, v81
	v_cvt_pk_bf16_f32 v88, v70, v71
	v_pk_fma_f32 v[100:101], v[94:95], v[94:95], v[100:101]
	v_and_b32_e32 v111, 0xffff0000, v83
	v_and_b32_e32 v110, 0xffff0000, v82
	v_cvt_pk_bf16_f32 v80, v72, v73
	v_cvt_pk_bf16_f32 v81, v76, v77
	v_lshlrev_b32_e32 v76, 16, v84
	v_and_b32_e32 v77, 0xffff0000, v84
	v_lshlrev_b32_e32 v72, 16, v88
	v_pk_add_f32 v[100:101], v[100:101], v[100:101] op_sel_hi:[0,1]
	v_lshlrev_b32_e32 v109, 16, v83
	v_lshlrev_b32_e32 v108, 16, v82
	v_pk_mul_f32 v[112:113], v[110:111], v[110:111]
	v_lshlrev_b32_e32 v122, 16, v85
	v_cvt_pk_bf16_f32 v89, v68, v69
	v_pk_fma_f32 v[112:113], v[108:109], v[108:109], v[112:113]
	v_mul_f32_e32 v73, v76, v76
	v_mul_f32_e32 v121, v77, v77
	v_and_b32_e32 v123, 0xffff0000, v85
	v_mul_f32_e32 v100, v122, v122
	v_lshlrev_b32_e32 v142, 16, v81
	v_mov_b32_e32 v120, v72
	v_and_b32_e32 v55, 0xffff0000, v88
	v_lshlrev_b32_e32 v70, 16, v89
	v_and_b32_e32 v71, 0xffff0000, v89
	v_and_b32_e32 v105, 0xffff0000, v87
	v_and_b32_e32 v104, 0xffff0000, v86
	v_pk_add_f32 v[112:113], v[112:113], v[112:113] op_sel_hi:[0,1]
	v_and_b32_e32 v117, 0xffff0000, v79
	v_and_b32_e32 v116, 0xffff0000, v78
	v_pk_fma_f32 v[124:125], v[122:123], v[122:123], v[100:101] op_sel_hi:[1,1,0]
	v_and_b32_e32 v143, 0xffff0000, v81
	v_mul_f32_e32 v100, v142, v142
	v_pk_add_f32 v[120:121], v[72:73], v[120:121]
	v_lshlrev_b32_e32 v74, 16, v80
	v_and_b32_e32 v75, 0xffff0000, v80
	v_lshlrev_b32_e32 v68, 16, v90
	v_lshlrev_b32_e32 v103, 16, v87
	v_lshlrev_b32_e32 v102, 16, v86
	v_pk_mul_f32 v[106:107], v[104:105], v[104:105]
	v_lshlrev_b32_e32 v115, 16, v79
	v_lshlrev_b32_e32 v114, 16, v78
	v_pk_mul_f32 v[118:119], v[116:117], v[116:117]
	v_pk_fma_f32 v[144:145], v[142:143], v[142:143], v[100:101] op_sel_hi:[1,1,0]
	v_mul_f32_e32 v124, v55, v55
	v_mul_f32_e32 v100, v70, v70
	v_mul_f32_e32 v112, v71, v71
	v_mul_f32_e32 v154, v72, v72
	v_mov_b32_e32 v155, v121
	v_cvt_pk_bf16_f32 v91, v66, v67
	v_pk_fma_f32 v[106:107], v[102:103], v[102:103], v[106:107]
	v_pk_fma_f32 v[118:119], v[114:115], v[114:115], v[118:119]
	v_mul_f32_e32 v69, v74, v74
	v_mul_f32_e32 v127, v75, v75
	v_pk_add_f32 v[120:121], v[154:155], v[124:125]
	v_pk_add_f32 v[100:101], v[100:101], v[112:113]
	v_mov_b32_e32 v126, v68
	v_and_b32_e32 v153, 0xffff0000, v90
	v_lshlrev_b32_e32 v66, 16, v91
	v_and_b32_e32 v67, 0xffff0000, v91
	v_pk_add_f32 v[106:107], v[106:107], v[106:107] op_sel_hi:[0,1]
	v_pk_add_f32 v[118:119], v[118:119], v[118:119] op_sel_hi:[0,1]
	v_pk_add_f32 v[100:101], v[120:121], v[100:101]
	v_pk_add_f32 v[120:121], v[68:69], v[126:127]
	v_mul_f32_e32 v144, v153, v153
	v_mul_f32_e32 v106, v66, v66
	v_mul_f32_e32 v118, v67, v67
	v_mul_f32_e32 v112, v68, v68
	v_mov_b32_e32 v113, v121
	v_pk_add_f32 v[112:113], v[112:113], v[144:145]
	v_pk_add_f32 v[106:107], v[106:107], v[118:119]
	s_waitcnt vmcnt(3)
	v_pk_add_f32 v[28:29], v[28:29], 1.0 op_sel_hi:[1,0]
	v_pk_add_f32 v[106:107], v[112:113], v[106:107]
	v_mov_b32_e32 v113, v100
	v_mov_b32_e32 v112, v106
	v_mov_b32_e32 v100, v107
	v_pk_add_f32 v[100:101], v[112:113], v[100:101]
	v_mov_b32_e32 v240, v100
	v_mov_b32_e32 v241, v101
	s_nop 1
	v_add_f32_dpp v240, v240, v240 quad_perm:[1,0,3,2] row_mask:0xf bank_mask:0xf
	v_add_f32_dpp v241, v241, v241 quad_perm:[1,0,3,2] row_mask:0xf bank_mask:0xf
	s_nop 0
	v_add_f32_dpp v240, v240, v240 quad_perm:[2,3,0,1] row_mask:0xf bank_mask:0xf
	v_add_f32_dpp v241, v241, v241 quad_perm:[2,3,0,1] row_mask:0xf bank_mask:0xf
	s_nop 0
	v_add_f32_dpp v240, v240, v240 row_half_mirror row_mask:0xf bank_mask:0xf
	v_add_f32_dpp v241, v241, v241 row_half_mirror row_mask:0xf bank_mask:0xf
	s_nop 0
	v_add_f32_dpp v240, v240, v240 row_mirror row_mask:0xf bank_mask:0xf
	v_add_f32_dpp v241, v241, v241 row_mirror row_mask:0xf bank_mask:0xf
	v_mov_b32_e32 v242, v240
	v_mov_b32_e32 v243, v241
	s_nop 1
	v_permlane16_swap_b32_e32 v240, v242
	v_permlane16_swap_b32_e32 v241, v243
	v_add_f32_e32 v240, v240, v242
	v_add_f32_e32 v241, v241, v243
	v_mov_b32_e32 v242, v240
	v_mov_b32_e32 v243, v241
	s_nop 1
	v_permlane32_swap_b32_e32 v240, v242
	v_permlane32_swap_b32_e32 v241, v243
	v_add_f32_e32 v240, v240, v242
	v_add_f32_e32 v241, v241, v243
	v_pk_add_f32 v[30:31], v[30:31], 1.0 op_sel_hi:[1,0]
	v_pk_mul_f32 v[28:29], v[20:21], v[28:29]
	v_pk_mul_f32 v[30:31], v[22:23], v[30:31]
	v_pk_mul_f32 v[98:99], v[34:35], v[98:99]
	v_pk_mul_f32 v[0:1], v[32:33], v[0:1]
	global_load_dwordx4 v[32:35], v[64:65], off offset:1024
	s_waitcnt vmcnt(3)
	v_pk_add_f32 v[26:27], v[26:27], 1.0 op_sel_hi:[1,0]
	v_pk_add_f32 v[24:25], v[24:25], 1.0 op_sel_hi:[1,0]
	s_waitcnt vmcnt(2)
	v_pk_mul_f32 v[26:27], v[18:19], v[26:27]
	v_pk_mul_f32 v[24:25], v[16:17], v[24:25]
	v_pk_add_f32 v[10:11], v[10:11], 1.0 op_sel_hi:[1,0]
	v_pk_add_f32 v[8:9], v[8:9], 1.0 op_sel_hi:[1,0]
	global_load_dwordx4 v[16:19], v[64:65], off offset:2048
	global_load_dwordx4 v[20:23], v[64:65], off offset:3072
	s_waitcnt vmcnt(3)
	v_pk_mul_f32 v[10:11], v[14:15], v[10:11]
	v_pk_mul_f32 v[8:9], v[12:13], v[8:9]
	global_store_dwordx2 v[62:63], v[92:93], off offset:2048
	global_store_dwordx2 v[60:61], v[86:87], off offset:2048
	global_store_dwordx2 v[62:63], v[82:83], off offset:2560
	global_store_dwordx2 v[60:61], v[78:79], off offset:2560
	global_store_dwordx2 v[62:63], v[84:85], off offset:3072
	global_store_dwordx2 v[60:61], v[80:81], off offset:3072
	global_store_dwordx2 v[62:63], v[88:89], off offset:3584
	v_mov_b32_e32 v62, v102
	v_mov_b32_e32 v63, v104
	v_mov_b32_e32 v104, v103
	global_store_dwordx2 v[60:61], v[90:91], off offset:3584
	v_mov_b32_e32 v73, v55
	v_mov_b32_e32 v69, v153
	v_mov_b32_e32 v12, v240
	v_mov_b32_e32 v13, v241
	s_nop 0
	v_pk_fma_f32 v[2:3], v[12:13], s[6:7], v[2:3] op_sel_hi:[1,0,0]
	v_mov_b32_e32 v14, v94
	v_mul_f32_e32 v12, 0x4b800000, v3
	v_cmp_gt_f32_e32 vcc, s0, v3
	v_cmp_gt_f32_e64 s[4:5], s0, v2
	v_mov_b32_e32 v15, v96
	v_cndmask_b32_e32 v3, v3, v12, vcc
	v_mul_f32_e32 v12, 0x4b800000, v2
	v_rsq_f32_e32 v3, v3
	v_cndmask_b32_e64 v2, v2, v12, s[4:5]
	v_rsq_f32_e32 v12, v2
	v_mov_b32_e32 v96, v95
	v_mul_f32_e32 v2, 0x45800000, v3
	v_cndmask_b32_e32 v2, v3, v2, vcc
	v_mul_f32_e32 v3, 0x45800000, v12
	v_cndmask_b32_e64 v12, v12, v3, s[4:5]
	v_pk_mul_f32 v[14:15], v[2:3], v[14:15] op_sel_hi:[0,1]
	v_pk_mul_f32 v[60:61], v[2:3], v[96:97] op_sel_hi:[0,1]
	v_pk_mul_f32 v[62:63], v[12:13], v[62:63] op_sel_hi:[0,1]
	v_pk_mul_f32 v[64:65], v[12:13], v[104:105] op_sel_hi:[0,1]
	v_pk_fma_f32 v[60:61], v[98:99], v[60:61], v[6:7]
	v_pk_fma_f32 v[14:15], v[0:1], v[14:15], v[4:5]
	v_pk_fma_f32 v[6:7], v[98:99], v[64:65], v[6:7]
	v_pk_fma_f32 v[0:1], v[0:1], v[62:63], v[4:5]
	s_mov_b32 s0, 0x5280000
	v_cvt_pk_bf16_f32 v0, v0, v1
	v_cvt_pk_bf16_f32 v1, v6, v7
	v_add_co_u32_e32 v6, vcc, s0, v58
	v_cvt_pk_bf16_f32 v4, v14, v15
	v_cvt_pk_bf16_f32 v5, v60, v61
	v_addc_co_u32_e32 v7, vcc, 0, v59, vcc
	global_store_dwordx2 v[6:7], v[4:5], off
	v_add_co_u32_e32 v4, vcc, s0, v56
	v_mov_b32_e32 v56, v114
	s_nop 0
	v_addc_co_u32_e32 v5, vcc, 0, v57, vcc
	global_store_dwordx2 v[4:5], v[0:1], off
	v_mov_b32_e32 v0, v108
	v_mov_b32_e32 v1, v110
	v_mov_b32_e32 v110, v109
	v_mov_b32_e32 v57, v116
	v_mov_b32_e32 v116, v115
	v_pk_mul_f32 v[0:1], v[2:3], v[0:1] op_sel_hi:[0,1]
	v_pk_mul_f32 v[14:15], v[2:3], v[110:111] op_sel_hi:[0,1]
	v_pk_mul_f32 v[56:57], v[12:13], v[56:57] op_sel_hi:[0,1]
	v_pk_mul_f32 v[58:59], v[12:13], v[116:117] op_sel_hi:[0,1]
	s_waitcnt vmcnt(12)
	v_pk_fma_f32 v[14:15], v[30:31], v[14:15], v[34:35]
	v_pk_fma_f32 v[0:1], v[28:29], v[0:1], v[32:33]
	v_pk_fma_f32 v[30:31], v[30:31], v[58:59], v[34:35]
	v_pk_fma_f32 v[28:29], v[28:29], v[56:57], v[32:33]
	v_cvt_pk_bf16_f32 v0, v0, v1
	v_cvt_pk_bf16_f32 v1, v14, v15
	v_cvt_pk_bf16_f32 v14, v28, v29
	v_cvt_pk_bf16_f32 v15, v30, v31
	global_store_dwordx2 v[6:7], v[0:1], off offset:512
	global_store_dwordx2 v[4:5], v[14:15], off offset:512
	v_pk_mul_f32 v[0:1], v[76:77], v[2:3] op_sel_hi:[1,0]
	v_pk_mul_f32 v[14:15], v[122:123], v[2:3] op_sel_hi:[1,0]
	s_waitcnt vmcnt(13)
	v_pk_fma_f32 v[0:1], v[24:25], v[0:1], v[16:17]
	v_pk_fma_f32 v[14:15], v[26:27], v[14:15], v[18:19]
	v_pk_mul_f32 v[28:29], v[74:75], v[12:13] op_sel_hi:[1,0]
	v_pk_mul_f32 v[30:31], v[142:143], v[12:13] op_sel_hi:[1,0]
	v_pk_fma_f32 v[16:17], v[24:25], v[28:29], v[16:17]
	v_pk_fma_f32 v[18:19], v[26:27], v[30:31], v[18:19]
	v_cvt_pk_bf16_f32 v0, v0, v1
	v_cvt_pk_bf16_f32 v1, v14, v15
	s_mov_b64 s[0:1], 0x800000
	v_cvt_pk_bf16_f32 v14, v16, v17
	v_cvt_pk_bf16_f32 v15, v18, v19
	global_store_dwordx2 v[6:7], v[0:1], off offset:1024
	global_store_dwordx2 v[4:5], v[14:15], off offset:1024
	v_pk_mul_f32 v[0:1], v[72:73], v[2:3] op_sel_hi:[1,0]
	v_pk_mul_f32 v[2:3], v[70:71], v[2:3] op_sel_hi:[1,0]
	v_lshl_add_u64 v[46:47], v[46:47], 0, s[0:1]
	v_lshl_add_u64 v[50:51], v[50:51], 0, s[0:1]
	s_mov_b32 s0, 0x8fff
	s_waitcnt vmcnt(14)
	v_pk_fma_f32 v[2:3], v[10:11], v[2:3], v[22:23]
	v_pk_fma_f32 v[0:1], v[8:9], v[0:1], v[20:21]
	v_pk_mul_f32 v[14:15], v[68:69], v[12:13] op_sel_hi:[1,0]
	v_pk_mul_f32 v[12:13], v[66:67], v[12:13] op_sel_hi:[1,0]
	s_mov_b64 s[4:5], 0x1000000
	v_cmp_lt_i32_e32 vcc, s0, v152
	v_pk_fma_f32 v[10:11], v[10:11], v[12:13], v[22:23]
	v_pk_fma_f32 v[8:9], v[8:9], v[14:15], v[20:21]
	v_cvt_pk_bf16_f32 v0, v0, v1
	v_cvt_pk_bf16_f32 v1, v2, v3
	v_lshl_add_u64 v[48:49], v[48:49], 0, s[4:5]
	s_or_b64 s[10:11], vcc, s[10:11]
	v_lshl_add_u64 v[52:53], v[52:53], 0, s[4:5]
	v_cvt_pk_bf16_f32 v2, v8, v9
	v_cvt_pk_bf16_f32 v3, v10, v11
	global_store_dwordx2 v[6:7], v[0:1], off offset:1536
	global_store_dwordx2 v[4:5], v[2:3], off offset:1536
	s_andn2_b64 exec, exec, s[10:11]
	s_cbranch_execz .LBB0_131

.LBB0_146:
	s_or_b64 exec, exec, s[4:5]
	v_add_u32_e32 v16, 0xffffe000, v8
	v_lshl_add_u64 v[0:1], v[0:1], 0, v[130:131]
	v_lshrrev_b32_e32 v9, 12, v16
	s_movk_i32 s0, 0x2000
	global_load_dwordx4 v[20:23], v[0:1], off
	global_load_dwordx4 v[12:15], v[0:1], off offset:1024
	global_load_dwordx4 v[4:7], v[0:1], off offset:2048
	s_nop 0
	global_load_dwordx4 v[0:3], v[0:1], off offset:3072
	v_lshl_add_u64 v[10:11], v[38:39], 0, s[10:11]
	v_add_u32_e32 v9, 1, v9
	v_cmp_gt_i32_e32 vcc, s0, v8
	v_mov_b32_e32 v17, s19
	v_mov_b32_e32 v18, s17
	v_mov_b32_e32 v19, s18
	v_mov_b32_e32 v24, s16
	v_cndmask_b32_e64 v72, v9, 0, vcc
	v_cndmask_b32_e32 v9, 0, v11, vcc
	v_cndmask_b32_e32 v8, v16, v10, vcc
	v_cndmask_b32_e32 v11, v17, v18, vcc
	v_cndmask_b32_e32 v10, v19, v24, vcc
	v_lshlrev_b64 v[8:9], 12, v[8:9]
	v_lshl_add_u64 v[8:9], v[10:11], 0, v[8:9]
	v_lshl_add_u64 v[16:17], v[8:9], 0, v[130:131]
	global_load_dwordx4 v[28:31], v[16:17], off
	global_load_dwordx4 v[24:27], v[16:17], off offset:1024
	global_load_dwordx4 v[8:11], v[16:17], off offset:3072
	s_nop 0
	global_load_dwordx4 v[16:19], v[16:17], off offset:2048
	v_mov_b64_e32 v[70:71], s[24:25]
	s_mov_b32 s0, 0x9000
	v_mad_u64_u32 v[70:71], s[0:1], v72, s0, v[70:71]
	v_lshl_add_u64 v[98:99], v[70:71], 0, v[130:131]
	s_mov_b64 s[0:1], 0x1000
	v_lshl_add_u64 v[90:91], v[98:99], 0, s[0:1]
	s_movk_i32 s0, 0x1000
	v_add_co_u32_e32 v70, vcc, s0, v98
	global_load_dwordx4 v[54:57], v[34:35], off
	global_load_dwordx4 v[58:61], v[34:35], off offset:1024
	global_load_dwordx4 v[62:65], v[34:35], off offset:2048
	global_load_dwordx4 v[66:69], v[34:35], off offset:3072
	v_addc_co_u32_e32 v71, vcc, 0, v99, vcc
	global_load_dwordx4 v[70:73], v[70:71], off
	s_nop 0
	global_load_dwordx4 v[74:77], v[98:99], off
	global_load_dwordx4 v[78:81], v[98:99], off offset:1024
	global_load_dwordx4 v[82:85], v[90:91], off offset:1024
	global_load_dwordx4 v[86:89], v[90:91], off offset:2048
	s_nop 0
	global_load_dwordx4 v[90:93], v[90:91], off offset:3072
	s_mov_b32 s0, 0x3a800000
	v_lshlrev_b64 v[46:47], 11, v[46:47]
	v_lshl_add_u64 v[46:47], v[36:37], 0, v[46:47]
	s_add_u32 s10, s10, 0x1000
	s_addc_u32 s11, s11, 0
	s_waitcnt vmcnt(17)
	v_pk_mul_f32 v[94:95], v[22:23], v[22:23]
	v_pk_mul_f32 v[96:97], v[20:21], v[20:21]
	s_waitcnt vmcnt(16)
	v_pk_mul_f32 v[100:101], v[14:15], v[14:15]
	v_pk_mul_f32 v[102:103], v[12:13], v[12:13]
	v_pk_mov_b32 v[106:107], v[96:97], v[94:95] op_sel:[1,0]
	v_mov_b32_e32 v97, v95
	v_pk_mov_b32 v[94:95], v[102:103], v[100:101] op_sel:[1,0]
	v_mov_b32_e32 v103, v101
	v_pk_add_f32 v[96:97], v[106:107], v[96:97]
	v_pk_add_f32 v[94:95], v[94:95], v[102:103]
	s_waitcnt vmcnt(14)
	v_mul_f32_e32 v105, v0, v0
	v_mul_f32_e32 v108, v1, v1
	v_pk_add_f32 v[96:97], v[96:97], v[96:97] op_sel:[0,1] op_sel_hi:[1,0]
	v_pk_add_f32 v[94:95], v[94:95], v[94:95] op_sel:[0,1] op_sel_hi:[1,0]
	v_mul_f32_e32 v104, v5, v5
	v_mov_b32_e32 v97, v105
	v_mov_b32_e32 v95, v108
	v_pk_fma_f32 v[100:101], v[4:5], v[4:5], v[104:105] op_sel_hi:[1,1,0]
	v_pk_add_f32 v[94:95], v[96:97], v[94:95]
	s_waitcnt vmcnt(13)
	v_pk_mul_f32 v[96:97], v[30:31], v[30:31]
	v_pk_mul_f32 v[102:103], v[28:29], v[28:29]
	s_waitcnt vmcnt(12)
	v_pk_mul_f32 v[104:105], v[26:27], v[26:27]
	v_pk_mul_f32 v[106:107], v[24:25], v[24:25]
	v_pk_mov_b32 v[112:113], v[102:103], v[96:97] op_sel:[1,0]
	v_mov_b32_e32 v103, v97
	v_pk_mov_b32 v[96:97], v[106:107], v[104:105] op_sel:[1,0]
	v_mov_b32_e32 v107, v105
	v_pk_add_f32 v[102:103], v[112:113], v[102:103]
	v_pk_add_f32 v[96:97], v[96:97], v[106:107]
	s_waitcnt vmcnt(11)
	v_mul_f32_e32 v114, v8, v8
	v_mul_f32_e32 v115, v9, v9
	v_pk_add_f32 v[102:103], v[102:103], v[102:103] op_sel:[0,1] op_sel_hi:[1,0]
	v_pk_add_f32 v[96:97], v[96:97], v[96:97] op_sel:[0,1] op_sel_hi:[1,0]
	v_mov_b32_e32 v103, v114
	v_mov_b32_e32 v97, v115
	v_mul_f32_e32 v109, v2, v2
	v_mul_f32_e32 v111, v3, v3
	s_waitcnt vmcnt(10)
	v_mul_f32_e32 v108, v17, v17
	v_mul_f32_e32 v110, v19, v19
	v_pk_add_f32 v[96:97], v[102:103], v[96:97]
	v_mul_f32_e32 v102, v7, v7
	v_mov_b32_e32 v101, v109
	v_mul_f32_e32 v116, v10, v10
	v_mul_f32_e32 v117, v11, v11
	v_pk_fma_f32 v[104:105], v[16:17], v[16:17], v[108:109] op_sel_hi:[1,1,0]
	v_pk_fma_f32 v[108:109], v[18:19], v[18:19], v[110:111] op_sel_hi:[1,1,0]
	v_pk_fma_f32 v[102:103], v[6:7], v[6:7], v[102:103] op_sel_hi:[1,1,0]
	v_mov_b32_e32 v105, v116
	v_mov_b32_e32 v109, v117
	v_mov_b32_e32 v103, v111
	v_pk_add_f32 v[104:105], v[104:105], v[108:109]
	v_pk_add_f32 v[100:101], v[100:101], v[102:103]
	v_pk_add_f32 v[96:97], v[96:97], v[104:105]
	v_pk_add_f32 v[94:95], v[94:95], v[100:101]
	v_mov_b32_e32 v101, v96
	v_mov_b32_e32 v100, v94
	v_mov_b32_e32 v96, v95
	v_pk_add_f32 v[100:101], v[100:101], v[96:97]
	global_load_dwordx4 v[94:97], v[98:99], off offset:2048
	s_waitcnt vmcnt(6)
	v_pk_add_f32 v[72:73], v[72:73], 1.0 op_sel_hi:[1,0]
	v_pk_add_f32 v[104:105], v[70:71], 1.0 op_sel_hi:[1,0]
	v_pk_mul_f32 v[56:57], v[56:57], v[72:73]
	global_load_dwordx4 v[70:73], v[98:99], off offset:3072
	v_mov_b32_e32 v240, v100
	v_mov_b32_e32 v241, v101
	s_nop 1
	v_add_f32_dpp v240, v240, v240 quad_perm:[1,0,3,2] row_mask:0xf bank_mask:0xf
	v_add_f32_dpp v241, v241, v241 quad_perm:[1,0,3,2] row_mask:0xf bank_mask:0xf
	s_nop 0
	v_add_f32_dpp v240, v240, v240 quad_perm:[2,3,0,1] row_mask:0xf bank_mask:0xf
	v_add_f32_dpp v241, v241, v241 quad_perm:[2,3,0,1] row_mask:0xf bank_mask:0xf
	s_nop 0
	v_add_f32_dpp v240, v240, v240 row_half_mirror row_mask:0xf bank_mask:0xf
	v_add_f32_dpp v241, v241, v241 row_half_mirror row_mask:0xf bank_mask:0xf
	s_nop 0
	v_add_f32_dpp v240, v240, v240 row_mirror row_mask:0xf bank_mask:0xf
	v_add_f32_dpp v241, v241, v241 row_mirror row_mask:0xf bank_mask:0xf
	v_mov_b32_e32 v242, v240
	v_mov_b32_e32 v243, v241
	s_nop 1
	v_permlane16_swap_b32_e32 v240, v242
	v_permlane16_swap_b32_e32 v241, v243
	v_add_f32_e32 v240, v240, v242
	v_add_f32_e32 v241, v241, v243
	v_mov_b32_e32 v242, v240
	v_mov_b32_e32 v243, v241
	s_nop 1
	v_permlane32_swap_b32_e32 v240, v242
	v_permlane32_swap_b32_e32 v241, v243
	v_add_f32_e32 v240, v240, v242
	v_add_f32_e32 v241, v241, v243
	s_waitcnt vmcnt(4)
	v_pk_add_f32 v[84:85], v[84:85], 1.0 op_sel_hi:[1,0]
	v_pk_add_f32 v[82:83], v[82:83], 1.0 op_sel_hi:[1,0]
	v_pk_mul_f32 v[60:61], v[60:61], v[84:85]
	v_pk_mul_f32 v[58:59], v[58:59], v[82:83]
	s_waitcnt vmcnt(3)
	v_pk_add_f32 v[82:83], v[88:89], 1.0 op_sel_hi:[1,0]
	v_pk_mul_f32 v[54:55], v[54:55], v[104:105]
	v_pk_mul_f32 v[64:65], v[64:65], v[82:83]
	v_pk_add_f32 v[86:87], v[86:87], 1.0 op_sel_hi:[1,0]
	v_pk_mul_f32 v[62:63], v[62:63], v[86:87]
	s_waitcnt vmcnt(2)
	v_pk_add_f32 v[86:87], v[92:93], 1.0 op_sel_hi:[1,0]
	v_pk_add_f32 v[88:89], v[90:91], 1.0 op_sel_hi:[1,0]
	v_pk_mul_f32 v[68:69], v[68:69], v[86:87]
	v_pk_mul_f32 v[66:67], v[66:67], v[88:89]
	v_mov_b32_e32 v82, v240
	v_mov_b32_e32 v83, v241
	s_nop 0
	v_pk_fma_f32 v[82:83], v[82:83], s[0:1], v[132:133] op_sel_hi:[1,0,0]
	s_mov_b32 s0, 0x800000
	v_mul_f32_e32 v84, 0x4b800000, v83
	v_cmp_gt_f32_e32 vcc, s0, v83
	v_cmp_gt_f32_e64 s[4:5], s0, v82
	s_mov_b64 s[0:1], 0x800000
	v_cndmask_b32_e32 v83, v83, v84, vcc
	v_mul_f32_e32 v84, 0x4b800000, v82
	v_rsq_f32_e32 v83, v83
	v_cndmask_b32_e64 v82, v82, v84, s[4:5]
	v_rsq_f32_e32 v84, v82
	v_mul_f32_e32 v82, 0x45800000, v83
	v_cndmask_b32_e32 v82, v83, v82, vcc
	v_mul_f32_e32 v83, 0x45800000, v84
	v_cndmask_b32_e64 v84, v84, v83, s[4:5]
	v_pk_mul_f32 v[28:29], v[28:29], v[82:83] op_sel_hi:[1,0]
	v_pk_mul_f32 v[30:31], v[30:31], v[82:83] op_sel_hi:[1,0]
	v_pk_mul_f32 v[20:21], v[20:21], v[84:85] op_sel_hi:[1,0]
	v_pk_mul_f32 v[22:23], v[22:23], v[84:85] op_sel_hi:[1,0]
	v_pk_fma_f32 v[30:31], v[56:57], v[30:31], v[76:77]
	v_pk_fma_f32 v[28:29], v[54:55], v[28:29], v[74:75]
	v_pk_fma_f32 v[22:23], v[56:57], v[22:23], v[76:77]
	v_pk_fma_f32 v[20:21], v[54:55], v[20:21], v[74:75]
	v_cvt_pk_bf16_f32 v28, v28, v29
	v_cvt_pk_bf16_f32 v29, v30, v31
	v_cvt_pk_bf16_f32 v20, v20, v21
	v_cvt_pk_bf16_f32 v21, v22, v23
	global_store_dwordx2 v[40:41], v[28:29], off
	global_store_dwordx2 v[46:47], v[20:21], off
	v_pk_mul_f32 v[20:21], v[24:25], v[82:83] op_sel_hi:[1,0]
	v_pk_mul_f32 v[22:23], v[26:27], v[82:83] op_sel_hi:[1,0]
	v_pk_mul_f32 v[12:13], v[12:13], v[84:85] op_sel_hi:[1,0]
	v_pk_mul_f32 v[14:15], v[14:15], v[84:85] op_sel_hi:[1,0]
	v_pk_fma_f32 v[22:23], v[60:61], v[22:23], v[80:81]
	v_pk_fma_f32 v[20:21], v[58:59], v[20:21], v[78:79]
	v_pk_fma_f32 v[14:15], v[60:61], v[14:15], v[80:81]
	v_pk_fma_f32 v[12:13], v[58:59], v[12:13], v[78:79]
	v_cvt_pk_bf16_f32 v20, v20, v21
	v_cvt_pk_bf16_f32 v21, v22, v23
	v_cvt_pk_bf16_f32 v12, v12, v13
	v_cvt_pk_bf16_f32 v13, v14, v15
	global_store_dwordx2 v[40:41], v[20:21], off offset:512
	global_store_dwordx2 v[46:47], v[12:13], off offset:512
	v_pk_mul_f32 v[12:13], v[16:17], v[82:83] op_sel_hi:[1,0]
	v_pk_mul_f32 v[14:15], v[18:19], v[82:83] op_sel_hi:[1,0]
	v_pk_mul_f32 v[4:5], v[4:5], v[84:85] op_sel_hi:[1,0]
	v_pk_mul_f32 v[6:7], v[6:7], v[84:85] op_sel_hi:[1,0]
	s_waitcnt vmcnt(5)
	v_pk_fma_f32 v[14:15], v[64:65], v[14:15], v[96:97]
	v_pk_fma_f32 v[12:13], v[62:63], v[12:13], v[94:95]
	v_pk_fma_f32 v[6:7], v[64:65], v[6:7], v[96:97]
	v_pk_fma_f32 v[4:5], v[62:63], v[4:5], v[94:95]
	v_cvt_pk_bf16_f32 v12, v12, v13
	v_cvt_pk_bf16_f32 v13, v14, v15
	v_cvt_pk_bf16_f32 v4, v4, v5
	v_cvt_pk_bf16_f32 v5, v6, v7
	global_store_dwordx2 v[40:41], v[12:13], off offset:1024
	global_store_dwordx2 v[46:47], v[4:5], off offset:1024
	v_pk_mul_f32 v[4:5], v[8:9], v[82:83] op_sel_hi:[1,0]
	v_pk_mul_f32 v[6:7], v[10:11], v[82:83] op_sel_hi:[1,0]
	v_pk_mul_f32 v[0:1], v[0:1], v[84:85] op_sel_hi:[1,0]
	s_waitcnt vmcnt(6)
	v_pk_fma_f32 v[6:7], v[68:69], v[6:7], v[72:73]
	v_pk_fma_f32 v[4:5], v[66:67], v[4:5], v[70:71]
	v_pk_mul_f32 v[2:3], v[2:3], v[84:85] op_sel_hi:[1,0]
	v_pk_fma_f32 v[0:1], v[66:67], v[0:1], v[70:71]
	v_pk_fma_f32 v[2:3], v[68:69], v[2:3], v[72:73]
	v_cvt_pk_bf16_f32 v4, v4, v5
	v_cvt_pk_bf16_f32 v5, v6, v7
	v_cvt_pk_bf16_f32 v0, v0, v1
	v_cvt_pk_bf16_f32 v1, v2, v3
	global_store_dwordx2 v[40:41], v[4:5], off offset:1536
	global_store_dwordx2 v[46:47], v[0:1], off offset:1536
	v_add_u32_e32 v0, s10, v32
	v_add_u32_e32 v0, 0xfffff000, v0
	v_lshl_add_u64 v[40:41], v[40:41], 0, s[0:1]
	s_mov_b32 s0, 0x8fff
	v_cmp_lt_i32_e32 vcc, s0, v0
	s_mov_b64 s[0:1], 0x1000000
	s_or_b64 s[8:9], vcc, s[8:9]
	v_lshl_add_u64 v[44:45], v[44:45], 0, s[0:1]
	s_andn2_b64 exec, exec, s[8:9]
	s_cbranch_execz .LBB0_151

.LBB0_373:
	s_or_b64 exec, exec, s[4:5]
	v_add_u32_e32 v12, 0x6000, v130
	v_ashrrev_i32_e32 v12, 12, v12
	s_movk_i32 s0, 0x1fff
	v_add_u32_e32 v12, 1, v12
	v_cmp_lt_i32_e32 vcc, s0, v152
	s_waitcnt vmcnt(13)
	v_lshlrev_b32_e32 v74, 16, v0
	v_and_b32_e32 v75, 0xffff0000, v0
	v_cndmask_b32_e32 v0, 0, v12, vcc
	v_lshlrev_b32_e32 v80, 16, v1
	v_and_b32_e32 v81, 0xffff0000, v1
	v_mul_hi_i32_i24_e32 v1, 0x2400, v0
	v_mul_i32_i24_e32 v0, 0x2400, v0
	v_lshlrev_b64 v[0:1], 2, v[0:1]
	s_waitcnt vmcnt(9)
	v_lshlrev_b32_e32 v72, 16, v2
	v_and_b32_e32 v73, 0xffff0000, v2
	v_lshlrev_b32_e32 v76, 16, v3
	v_and_b32_e32 v77, 0xffff0000, v3
	v_lshl_add_u64 v[2:3], v[40:41], 0, v[0:1]
	v_lshlrev_b32_e32 v92, 16, v8
	v_and_b32_e32 v93, 0xffff0000, v8
	v_lshlrev_b32_e32 v94, 16, v9
	v_and_b32_e32 v95, 0xffff0000, v9
	v_lshlrev_b32_e32 v86, 16, v10
	v_and_b32_e32 v87, 0xffff0000, v10
	v_lshlrev_b32_e32 v90, 16, v11
	v_and_b32_e32 v91, 0xffff0000, v11
	v_lshlrev_b32_e32 v82, 16, v4
	v_and_b32_e32 v83, 0xffff0000, v4
	v_lshlrev_b32_e32 v88, 16, v5
	v_and_b32_e32 v89, 0xffff0000, v5
	v_lshlrev_b32_e32 v78, 16, v6
	v_and_b32_e32 v79, 0xffff0000, v6
	v_lshlrev_b32_e32 v84, 16, v7
	v_and_b32_e32 v85, 0xffff0000, v7
	global_load_dwordx4 v[4:7], v[2:3], off
	global_load_dwordx4 v[8:11], v[2:3], off offset:1024
	global_load_dwordx4 v[20:23], v[42:43], off
	global_load_dwordx4 v[12:15], v[42:43], off offset:1024
	global_load_dwordx4 v[16:19], v[2:3], off offset:2048
	global_load_dwordx4 v[24:27], v[2:3], off offset:3072
	global_load_dwordx4 v[32:35], v[42:43], off offset:2048
	global_load_dwordx4 v[28:31], v[42:43], off offset:3072
	v_lshl_add_u64 v[0:1], s[10:11], 0, v[0:1]
	v_mov_b32_e32 v55, v131
	v_lshl_add_u64 v[64:65], v[0:1], 0, v[54:55]
	s_movk_i32 s0, 0x1000
	v_add_co_u32_e32 v0, vcc, s0, v64
	s_waitcnt vmcnt(15)
	v_lshlrev_b32_e32 v142, 16, v112
	v_addc_co_u32_e32 v1, vcc, 0, v65, vcc
	global_load_dwordx4 v[0:3], v[0:1], off
	v_and_b32_e32 v143, 0xffff0000, v112
	s_waitcnt vmcnt(15)
	v_lshlrev_b32_e32 v144, 16, v120
	v_and_b32_e32 v145, 0xffff0000, v120
	v_lshlrev_b32_e32 v112, 16, v113
	v_and_b32_e32 v113, 0xffff0000, v113
	v_lshlrev_b32_e32 v120, 16, v121
	v_and_b32_e32 v121, 0xffff0000, v121
	v_pk_add_f32 v[142:143], v[142:143], v[144:145]
	v_pk_add_f32 v[112:113], v[112:113], v[120:121]
	v_lshlrev_b32_e32 v120, 16, v96
	v_and_b32_e32 v121, 0xffff0000, v96
	v_lshlrev_b32_e32 v144, 16, v98
	v_and_b32_e32 v145, 0xffff0000, v98
	v_lshlrev_b32_e32 v96, 16, v97
	v_and_b32_e32 v97, 0xffff0000, v97
	v_lshlrev_b32_e32 v98, 16, v99
	v_and_b32_e32 v99, 0xffff0000, v99
	v_pk_add_f32 v[120:121], v[120:121], v[144:145]
	v_pk_add_f32 v[96:97], v[96:97], v[98:99]
	v_mov_b32_e32 v144, v143
	v_mov_b32_e32 v145, v113
	v_mov_b32_e32 v98, v142
	v_mov_b32_e32 v99, v112
	v_pk_mul_f32 v[144:145], v[144:145], v[144:145]
	v_mov_b32_e32 v154, v121
	v_mov_b32_e32 v155, v97
	v_pk_fma_f32 v[98:99], v[98:99], v[98:99], v[144:145]
	v_mov_b32_e32 v144, v120
	v_mov_b32_e32 v145, v96
	v_pk_mul_f32 v[154:155], v[154:155], v[154:155]
	s_waitcnt vmcnt(13)
	v_lshlrev_b32_e32 v156, 16, v124
	v_pk_fma_f32 v[144:145], v[144:145], v[144:145], v[154:155]
	v_and_b32_e32 v157, 0xffff0000, v124
	v_pk_add_f32 v[154:155], v[144:145], v[144:145] op_sel:[0,1] op_sel_hi:[1,0]
	v_lshlrev_b32_e32 v144, 16, v116
	v_and_b32_e32 v145, 0xffff0000, v116
	v_lshlrev_b32_e32 v116, 16, v117
	v_and_b32_e32 v117, 0xffff0000, v117
	v_lshlrev_b32_e32 v124, 16, v125
	v_and_b32_e32 v125, 0xffff0000, v125
	v_pk_add_f32 v[144:145], v[144:145], v[156:157]
	v_pk_add_f32 v[116:117], v[116:117], v[124:125]
	v_lshlrev_b32_e32 v124, 16, v108
	v_and_b32_e32 v125, 0xffff0000, v108
	v_lshlrev_b32_e32 v156, 16, v104
	v_and_b32_e32 v157, 0xffff0000, v104
	v_lshlrev_b32_e32 v108, 16, v109
	v_and_b32_e32 v109, 0xffff0000, v109
	v_lshlrev_b32_e32 v104, 16, v105
	v_and_b32_e32 v105, 0xffff0000, v105
	v_pk_add_f32 v[124:125], v[124:125], v[156:157]
	v_pk_add_f32 v[104:105], v[108:109], v[104:105]
	v_mov_b32_e32 v156, v145
	v_mov_b32_e32 v157, v117
	v_mov_b32_e32 v108, v144
	v_mov_b32_e32 v109, v116
	v_pk_mul_f32 v[156:157], v[156:157], v[156:157]
	v_mov_b32_e32 v170, v125
	v_mov_b32_e32 v171, v105
	v_pk_fma_f32 v[108:109], v[108:109], v[108:109], v[156:157]
	v_mov_b32_e32 v156, v124
	v_mov_b32_e32 v157, v104
	v_pk_mul_f32 v[170:171], v[170:171], v[170:171]
	s_waitcnt vmcnt(11)
	v_lshlrev_b32_e32 v178, 16, v122
	v_pk_fma_f32 v[156:157], v[156:157], v[156:157], v[170:171]
	v_lshlrev_b32_e32 v170, 16, v114
	v_and_b32_e32 v171, 0xffff0000, v114
	v_and_b32_e32 v179, 0xffff0000, v122
	v_pk_add_f32 v[170:171], v[170:171], v[178:179]
	v_lshlrev_b32_e32 v114, 16, v115
	v_and_b32_e32 v115, 0xffff0000, v115
	v_lshlrev_b32_e32 v122, 16, v123
	v_and_b32_e32 v123, 0xffff0000, v123
	v_lshlrev_b32_e32 v70, 16, v68
	v_and_b32_e32 v71, 0xffff0000, v68
	v_pk_add_f32 v[114:115], v[114:115], v[122:123]
	v_lshlrev_b32_e32 v122, 16, v102
	v_and_b32_e32 v123, 0xffff0000, v102
	v_lshlrev_b32_e32 v178, 16, v100
	v_and_b32_e32 v179, 0xffff0000, v100
	v_lshlrev_b32_e32 v102, 16, v103
	v_and_b32_e32 v103, 0xffff0000, v103
	v_lshlrev_b32_e32 v100, 16, v101
	v_and_b32_e32 v101, 0xffff0000, v101
	v_mul_f32_e32 v68, v171, v171
	s_waitcnt vmcnt(10)
	v_lshlrev_b32_e32 v186, 16, v118
	v_and_b32_e32 v187, 0xffff0000, v118
	s_waitcnt vmcnt(9)
	v_lshlrev_b32_e32 v188, 16, v126
	v_and_b32_e32 v189, 0xffff0000, v126
	v_lshlrev_b32_e32 v118, 16, v119
	v_and_b32_e32 v119, 0xffff0000, v119
	v_lshlrev_b32_e32 v126, 16, v127
	v_and_b32_e32 v127, 0xffff0000, v127
	v_pk_add_f32 v[100:101], v[102:103], v[100:101]
	v_pk_fma_f32 v[102:103], v[170:171], v[170:171], v[68:69] op_sel_hi:[1,1,0]
	v_mul_f32_e32 v68, v115, v115
	v_pk_add_f32 v[186:187], v[186:187], v[188:189]
	v_pk_add_f32 v[118:119], v[118:119], v[126:127]
	v_lshlrev_b32_e32 v126, 16, v110
	v_and_b32_e32 v127, 0xffff0000, v110
	v_lshlrev_b32_e32 v188, 16, v106
	v_and_b32_e32 v189, 0xffff0000, v106
	v_lshlrev_b32_e32 v110, 16, v111
	v_and_b32_e32 v111, 0xffff0000, v111
	v_lshlrev_b32_e32 v106, 16, v107
	v_and_b32_e32 v107, 0xffff0000, v107
	v_pk_add_f32 v[98:99], v[98:99], v[98:99] op_sel:[0,1] op_sel_hi:[1,0]
	v_pk_add_f32 v[108:109], v[108:109], v[108:109] op_sel:[0,1] op_sel_hi:[1,0]
	v_pk_add_f32 v[122:123], v[122:123], v[178:179]
	v_pk_fma_f32 v[178:179], v[114:115], v[114:115], v[68:69] op_sel_hi:[1,1,0]
	v_pk_add_f32 v[126:127], v[126:127], v[188:189]
	v_pk_add_f32 v[106:107], v[110:111], v[106:107]
	v_pk_mul_f32 v[110:111], v[186:187], v[186:187]
	v_pk_mul_f32 v[188:189], v[118:119], v[118:119]
	v_mul_f32_e32 v68, v123, v123
	v_mov_b32_e32 v99, v110
	v_mov_b32_e32 v109, v111
	v_mov_b32_e32 v103, v188
	v_mov_b32_e32 v179, v189
	v_pk_fma_f32 v[182:183], v[122:123], v[122:123], v[68:69] op_sel_hi:[1,1,0]
	v_mul_f32_e32 v68, v101, v101
	v_pk_add_f32 v[98:99], v[98:99], v[108:109]
	v_pk_add_f32 v[102:103], v[102:103], v[178:179]
	v_pk_add_f32 v[156:157], v[156:157], v[156:157] op_sel:[0,1] op_sel_hi:[1,0]
	v_pk_fma_f32 v[184:185], v[100:101], v[100:101], v[68:69] op_sel_hi:[1,1,0]
	v_pk_add_f32 v[98:99], v[98:99], v[102:103]
	v_pk_mul_f32 v[102:103], v[126:127], v[126:127]
	v_pk_mul_f32 v[108:109], v[106:107], v[106:107]
	v_mov_b32_e32 v155, v102
	v_mov_b32_e32 v157, v103
	v_mov_b32_e32 v183, v108
	v_mov_b32_e32 v185, v109
	v_pk_add_f32 v[102:103], v[154:155], v[156:157]
	v_pk_add_f32 v[108:109], v[182:183], v[184:185]
	s_waitcnt vmcnt(6)
	v_pk_mul_f32 v[154:155], v[4:5], v[20:21]
	v_pk_add_f32 v[102:103], v[102:103], v[108:109]
	v_mov_b32_e32 v109, v98
	v_mov_b32_e32 v108, v102
	v_mov_b32_e32 v98, v103
	v_pk_add_f32 v[98:99], v[108:109], v[98:99]
	v_mov_b32_e32 v240, v98
	v_mov_b32_e32 v241, v99
	s_nop 1
	v_add_f32_dpp v240, v240, v240 quad_perm:[1,0,3,2] row_mask:0xf bank_mask:0xf
	v_add_f32_dpp v241, v241, v241 quad_perm:[1,0,3,2] row_mask:0xf bank_mask:0xf
	s_nop 0
	v_add_f32_dpp v240, v240, v240 quad_perm:[2,3,0,1] row_mask:0xf bank_mask:0xf
	v_add_f32_dpp v241, v241, v241 quad_perm:[2,3,0,1] row_mask:0xf bank_mask:0xf
	s_nop 0
	v_add_f32_dpp v240, v240, v240 row_half_mirror row_mask:0xf bank_mask:0xf
	v_add_f32_dpp v241, v241, v241 row_half_mirror row_mask:0xf bank_mask:0xf
	s_nop 0
	v_add_f32_dpp v240, v240, v240 row_mirror row_mask:0xf bank_mask:0xf
	v_add_f32_dpp v241, v241, v241 row_mirror row_mask:0xf bank_mask:0xf
	v_mov_b32_e32 v242, v240
	v_mov_b32_e32 v243, v241
	s_nop 1
	v_permlane16_swap_b32_e32 v240, v242
	v_permlane16_swap_b32_e32 v241, v243
	v_add_f32_e32 v240, v240, v242
	v_add_f32_e32 v241, v241, v243
	v_mov_b32_e32 v242, v240
	v_mov_b32_e32 v243, v241
	s_nop 1
	v_permlane32_swap_b32_e32 v240, v242
	v_permlane32_swap_b32_e32 v241, v243
	v_add_f32_e32 v240, v240, v242
	v_add_f32_e32 v241, v241, v243
	v_pk_mul_f32 v[110:111], v[6:7], v[22:23]
	s_waitcnt vmcnt(5)
	v_pk_mul_f32 v[156:157], v[8:9], v[12:13]
	s_waitcnt vmcnt(2)
	v_pk_mul_f32 v[182:183], v[16:17], v[32:33]
	s_mov_b64 s[0:1], 0x1000
	v_lshl_add_u64 v[12:13], v[64:65], 0, s[0:1]
	v_pk_mul_f32 v[178:179], v[18:19], v[34:35]
	s_waitcnt vmcnt(1)
	v_pk_mul_f32 v[184:185], v[26:27], v[30:31]
	v_pk_mul_f32 v[188:189], v[24:25], v[28:29]
	v_pk_mul_f32 v[102:103], v[10:11], v[14:15]
	s_mov_b32 s0, 0x358637bd
	s_mov_b32 s6, 0x3a800000
	v_lshlrev_b32_e32 v108, 16, v66
	global_load_dwordx4 v[4:7], v[64:65], off
	v_and_b32_e32 v109, 0xffff0000, v66
	v_lshlrev_b32_e32 v68, 16, v69
	v_and_b32_e32 v69, 0xffff0000, v69
	global_load_dwordx4 v[8:11], v[12:13], off offset:3072
	global_load_dwordx4 v[32:35], v[44:45], off
	global_load_dwordx4 v[20:23], v[44:45], off offset:1024
	s_waitcnt vmcnt(4)
	v_pk_add_f32 v[98:99], v[2:3], 1.0 op_sel_hi:[1,0]
	v_lshlrev_b32_e32 v66, 16, v67
	global_load_dwordx4 v[28:31], v[12:13], off offset:1024
	global_load_dwordx4 v[24:27], v[12:13], off offset:2048
	global_load_dwordx4 v[16:19], v[44:45], off offset:2048
	s_nop 0
	global_load_dwordx4 v[12:15], v[44:45], off offset:3072
	v_and_b32_e32 v67, 0xffff0000, v67
	v_pk_add_f32 v[0:1], v[0:1], 1.0 op_sel_hi:[1,0]
	v_add_u32_e32 v130, 0x1000, v130
	v_mov_b32_e32 v190, v240
	v_mov_b32_e32 v191, v241
	v_mov_b64_e32 v[2:3], s[0:1]
	v_pk_fma_f32 v[190:191], v[190:191], s[6:7], v[2:3] op_sel_hi:[1,0,0]
	s_mov_b32 s0, 0x800000
	v_mul_f32_e32 v55, 0x4b800000, v191
	v_cmp_gt_f32_e32 vcc, s0, v191
	v_mul_f32_e32 v153, 0x4b800000, v190
	v_cmp_gt_f32_e64 s[4:5], s0, v190
	v_cndmask_b32_e32 v55, v191, v55, vcc
	v_rsq_f32_e32 v55, v55
	v_cndmask_b32_e64 v153, v190, v153, s[4:5]
	v_rsq_f32_e32 v153, v153
	v_mul_f32_e32 v181, 0x45800000, v55
	v_cndmask_b32_e32 v55, v55, v181, vcc
	v_mul_f32_e32 v190, 0.5, v55
	v_mul_f32_e32 v55, 0x45800000, v153
	v_cndmask_b32_e64 v55, v153, v55, s[4:5]
	v_mul_f32_e32 v192, 0.5, v55
	v_pk_mul_f32 v[96:97], v[96:97], v[192:193] op_sel_hi:[1,0]
	v_pk_mul_f32 v[142:143], v[142:143], v[190:191] op_sel_hi:[1,0]
	v_pk_fma_f32 v[90:91], v[110:111], v[96:97], v[90:91]
	v_pk_mul_f32 v[96:97], v[144:145], v[190:191] op_sel_hi:[1,0]
	v_pk_mul_f32 v[112:113], v[112:113], v[190:191] op_sel_hi:[1,0]
	v_pk_fma_f32 v[82:83], v[156:157], v[96:97], v[82:83]
	v_pk_mul_f32 v[96:97], v[124:125], v[192:193] op_sel_hi:[1,0]
	v_pk_fma_f32 v[94:95], v[110:111], v[112:113], v[94:95]
	v_pk_fma_f32 v[78:79], v[156:157], v[96:97], v[78:79]
	v_pk_mul_f32 v[96:97], v[170:171], v[190:191] op_sel_hi:[1,0]
	v_pk_fma_f32 v[92:93], v[154:155], v[142:143], v[92:93]
	v_pk_fma_f32 v[74:75], v[182:183], v[96:97], v[74:75]
	v_pk_mul_f32 v[96:97], v[122:123], v[192:193] op_sel_hi:[1,0]
	v_pk_mul_f32 v[112:113], v[120:121], v[192:193] op_sel_hi:[1,0]
	v_pk_fma_f32 v[72:73], v[182:183], v[96:97], v[72:73]
	v_pk_mul_f32 v[96:97], v[186:187], v[190:191] op_sel_hi:[1,0]
	v_pk_mul_f32 v[100:101], v[100:101], v[192:193] op_sel_hi:[1,0]
	v_pk_fma_f32 v[70:71], v[188:189], v[96:97], v[70:71]
	v_pk_mul_f32 v[96:97], v[126:127], v[192:193] op_sel_hi:[1,0]
	v_pk_fma_f32 v[86:87], v[154:155], v[112:113], v[86:87]
	v_pk_mul_f32 v[110:111], v[116:117], v[190:191] op_sel_hi:[1,0]
	v_pk_mul_f32 v[104:105], v[104:105], v[192:193] op_sel_hi:[1,0]
	v_pk_fma_f32 v[76:77], v[178:179], v[100:101], v[76:77]
	v_pk_mul_f32 v[100:101], v[118:119], v[190:191] op_sel_hi:[1,0]
	v_pk_fma_f32 v[96:97], v[188:189], v[96:97], v[108:109]
	v_cvt_pk_bf16_f32 v92, v92, v93
	v_cvt_pk_bf16_f32 v93, v94, v95
	v_pk_fma_f32 v[88:89], v[102:103], v[110:111], v[88:89]
	v_pk_fma_f32 v[84:85], v[102:103], v[104:105], v[84:85]
	v_pk_mul_f32 v[102:103], v[114:115], v[190:191] op_sel_hi:[1,0]
	v_pk_fma_f32 v[68:69], v[184:185], v[100:101], v[68:69]
	v_pk_mul_f32 v[100:101], v[106:107], v[192:193] op_sel_hi:[1,0]
	v_cvt_pk_bf16_f32 v86, v86, v87
	v_cvt_pk_bf16_f32 v87, v90, v91
	v_cvt_pk_bf16_f32 v90, v96, v97
	v_and_b32_e32 v97, 0xffff0000, v93
	v_and_b32_e32 v96, 0xffff0000, v92
	v_pk_fma_f32 v[80:81], v[178:179], v[102:103], v[80:81]
	v_pk_fma_f32 v[66:67], v[184:185], v[100:101], v[66:67]
	v_cvt_pk_bf16_f32 v82, v82, v83
	v_cvt_pk_bf16_f32 v83, v88, v89
	v_lshlrev_b32_e32 v95, 16, v93
	v_lshlrev_b32_e32 v94, 16, v92
	v_pk_mul_f32 v[100:101], v[96:97], v[96:97]
	v_cvt_pk_bf16_f32 v78, v78, v79
	v_cvt_pk_bf16_f32 v79, v84, v85
	v_cvt_pk_bf16_f32 v84, v74, v75
	v_cvt_pk_bf16_f32 v85, v80, v81
	v_cvt_pk_bf16_f32 v88, v70, v71
	v_pk_fma_f32 v[100:101], v[94:95], v[94:95], v[100:101]
	v_and_b32_e32 v111, 0xffff0000, v83
	v_and_b32_e32 v110, 0xffff0000, v82
	v_cvt_pk_bf16_f32 v80, v72, v73
	v_cvt_pk_bf16_f32 v81, v76, v77
	v_lshlrev_b32_e32 v76, 16, v84
	v_and_b32_e32 v77, 0xffff0000, v84
	v_lshlrev_b32_e32 v72, 16, v88
	v_pk_add_f32 v[100:101], v[100:101], v[100:101] op_sel_hi:[0,1]
	v_lshlrev_b32_e32 v109, 16, v83
	v_lshlrev_b32_e32 v108, 16, v82
	v_pk_mul_f32 v[112:113], v[110:111], v[110:111]
	v_lshlrev_b32_e32 v122, 16, v85
	v_cvt_pk_bf16_f32 v89, v68, v69
	v_pk_fma_f32 v[112:113], v[108:109], v[108:109], v[112:113]
	v_mul_f32_e32 v73, v76, v76
	v_mul_f32_e32 v121, v77, v77
	v_and_b32_e32 v123, 0xffff0000, v85
	v_mul_f32_e32 v100, v122, v122
	v_lshlrev_b32_e32 v142, 16, v81
	v_mov_b32_e32 v120, v72
	v_and_b32_e32 v55, 0xffff0000, v88
	v_lshlrev_b32_e32 v70, 16, v89
	v_and_b32_e32 v71, 0xffff0000, v89
	v_and_b32_e32 v105, 0xffff0000, v87
	v_and_b32_e32 v104, 0xffff0000, v86
	v_pk_add_f32 v[112:113], v[112:113], v[112:113] op_sel_hi:[0,1]
	v_and_b32_e32 v117, 0xffff0000, v79
	v_and_b32_e32 v116, 0xffff0000, v78
	v_pk_fma_f32 v[124:125], v[122:123], v[122:123], v[100:101] op_sel_hi:[1,1,0]
	v_and_b32_e32 v143, 0xffff0000, v81
	v_mul_f32_e32 v100, v142, v142
	v_pk_add_f32 v[120:121], v[72:73], v[120:121]
	v_lshlrev_b32_e32 v74, 16, v80
	v_and_b32_e32 v75, 0xffff0000, v80
	v_lshlrev_b32_e32 v68, 16, v90
	v_lshlrev_b32_e32 v103, 16, v87
	v_lshlrev_b32_e32 v102, 16, v86
	v_pk_mul_f32 v[106:107], v[104:105], v[104:105]
	v_lshlrev_b32_e32 v115, 16, v79
	v_lshlrev_b32_e32 v114, 16, v78
	v_pk_mul_f32 v[118:119], v[116:117], v[116:117]
	v_pk_fma_f32 v[144:145], v[142:143], v[142:143], v[100:101] op_sel_hi:[1,1,0]
	v_mul_f32_e32 v124, v55, v55
	v_mul_f32_e32 v100, v70, v70
	v_mul_f32_e32 v112, v71, v71
	v_mul_f32_e32 v154, v72, v72
	v_mov_b32_e32 v155, v121
	v_cvt_pk_bf16_f32 v91, v66, v67
	v_pk_fma_f32 v[106:107], v[102:103], v[102:103], v[106:107]
	v_pk_fma_f32 v[118:119], v[114:115], v[114:115], v[118:119]
	v_mul_f32_e32 v69, v74, v74
	v_mul_f32_e32 v127, v75, v75
	v_pk_add_f32 v[120:121], v[154:155], v[124:125]
	v_pk_add_f32 v[100:101], v[100:101], v[112:113]
	v_mov_b32_e32 v126, v68
	v_and_b32_e32 v153, 0xffff0000, v90
	v_lshlrev_b32_e32 v66, 16, v91
	v_and_b32_e32 v67, 0xffff0000, v91
	v_pk_add_f32 v[106:107], v[106:107], v[106:107] op_sel_hi:[0,1]
	v_pk_add_f32 v[118:119], v[118:119], v[118:119] op_sel_hi:[0,1]
	v_pk_add_f32 v[100:101], v[120:121], v[100:101]
	v_pk_add_f32 v[120:121], v[68:69], v[126:127]
	v_mul_f32_e32 v144, v153, v153
	v_mul_f32_e32 v106, v66, v66
	v_mul_f32_e32 v118, v67, v67
	v_mul_f32_e32 v112, v68, v68
	v_mov_b32_e32 v113, v121
	v_pk_add_f32 v[112:113], v[112:113], v[144:145]
	v_pk_add_f32 v[106:107], v[106:107], v[118:119]
	s_waitcnt vmcnt(3)
	v_pk_add_f32 v[28:29], v[28:29], 1.0 op_sel_hi:[1,0]
	v_pk_add_f32 v[106:107], v[112:113], v[106:107]
	v_mov_b32_e32 v113, v100
	v_mov_b32_e32 v112, v106
	v_mov_b32_e32 v100, v107
	v_pk_add_f32 v[100:101], v[112:113], v[100:101]
	v_mov_b32_e32 v240, v100
	v_mov_b32_e32 v241, v101
	s_nop 1
	v_add_f32_dpp v240, v240, v240 quad_perm:[1,0,3,2] row_mask:0xf bank_mask:0xf
	v_add_f32_dpp v241, v241, v241 quad_perm:[1,0,3,2] row_mask:0xf bank_mask:0xf
	s_nop 0
	v_add_f32_dpp v240, v240, v240 quad_perm:[2,3,0,1] row_mask:0xf bank_mask:0xf
	v_add_f32_dpp v241, v241, v241 quad_perm:[2,3,0,1] row_mask:0xf bank_mask:0xf
	s_nop 0
	v_add_f32_dpp v240, v240, v240 row_half_mirror row_mask:0xf bank_mask:0xf
	v_add_f32_dpp v241, v241, v241 row_half_mirror row_mask:0xf bank_mask:0xf
	s_nop 0
	v_add_f32_dpp v240, v240, v240 row_mirror row_mask:0xf bank_mask:0xf
	v_add_f32_dpp v241, v241, v241 row_mirror row_mask:0xf bank_mask:0xf
	v_mov_b32_e32 v242, v240
	v_mov_b32_e32 v243, v241
	s_nop 1
	v_permlane16_swap_b32_e32 v240, v242
	v_permlane16_swap_b32_e32 v241, v243
	v_add_f32_e32 v240, v240, v242
	v_add_f32_e32 v241, v241, v243
	v_mov_b32_e32 v242, v240
	v_mov_b32_e32 v243, v241
	s_nop 1
	v_permlane32_swap_b32_e32 v240, v242
	v_permlane32_swap_b32_e32 v241, v243
	v_add_f32_e32 v240, v240, v242
	v_add_f32_e32 v241, v241, v243
	v_pk_add_f32 v[30:31], v[30:31], 1.0 op_sel_hi:[1,0]
	v_pk_mul_f32 v[28:29], v[20:21], v[28:29]
	v_pk_mul_f32 v[30:31], v[22:23], v[30:31]
	v_pk_mul_f32 v[98:99], v[34:35], v[98:99]
	v_pk_mul_f32 v[0:1], v[32:33], v[0:1]
	global_load_dwordx4 v[32:35], v[64:65], off offset:1024
	s_waitcnt vmcnt(3)
	v_pk_add_f32 v[26:27], v[26:27], 1.0 op_sel_hi:[1,0]
	v_pk_add_f32 v[24:25], v[24:25], 1.0 op_sel_hi:[1,0]
	s_waitcnt vmcnt(2)
	v_pk_mul_f32 v[26:27], v[18:19], v[26:27]
	v_pk_mul_f32 v[24:25], v[16:17], v[24:25]
	v_pk_add_f32 v[10:11], v[10:11], 1.0 op_sel_hi:[1,0]
	v_pk_add_f32 v[8:9], v[8:9], 1.0 op_sel_hi:[1,0]
	global_load_dwordx4 v[16:19], v[64:65], off offset:2048
	global_load_dwordx4 v[20:23], v[64:65], off offset:3072
	s_waitcnt vmcnt(3)
	v_pk_mul_f32 v[10:11], v[14:15], v[10:11]
	v_pk_mul_f32 v[8:9], v[12:13], v[8:9]
	global_store_dwordx2 v[62:63], v[92:93], off offset:2048
	global_store_dwordx2 v[60:61], v[86:87], off offset:2048
	global_store_dwordx2 v[62:63], v[82:83], off offset:2560
	global_store_dwordx2 v[60:61], v[78:79], off offset:2560
	global_store_dwordx2 v[62:63], v[84:85], off offset:3072
	global_store_dwordx2 v[60:61], v[80:81], off offset:3072
	global_store_dwordx2 v[62:63], v[88:89], off offset:3584
	v_mov_b32_e32 v62, v102
	v_mov_b32_e32 v63, v104
	v_mov_b32_e32 v104, v103
	global_store_dwordx2 v[60:61], v[90:91], off offset:3584
	v_mov_b32_e32 v73, v55
	v_mov_b32_e32 v69, v153
	v_mov_b32_e32 v12, v240
	v_mov_b32_e32 v13, v241
	s_nop 0
	v_pk_fma_f32 v[2:3], v[12:13], s[6:7], v[2:3] op_sel_hi:[1,0,0]
	v_mov_b32_e32 v14, v94
	v_mul_f32_e32 v12, 0x4b800000, v3
	v_cmp_gt_f32_e32 vcc, s0, v3
	v_cmp_gt_f32_e64 s[4:5], s0, v2
	v_mov_b32_e32 v15, v96
	v_cndmask_b32_e32 v3, v3, v12, vcc
	v_mul_f32_e32 v12, 0x4b800000, v2
	v_rsq_f32_e32 v3, v3
	v_cndmask_b32_e64 v2, v2, v12, s[4:5]
	v_rsq_f32_e32 v12, v2
	v_mov_b32_e32 v96, v95
	v_mul_f32_e32 v2, 0x45800000, v3
	v_cndmask_b32_e32 v2, v3, v2, vcc
	v_mul_f32_e32 v3, 0x45800000, v12
	v_cndmask_b32_e64 v12, v12, v3, s[4:5]
	v_pk_mul_f32 v[14:15], v[2:3], v[14:15] op_sel_hi:[0,1]
	v_pk_mul_f32 v[60:61], v[2:3], v[96:97] op_sel_hi:[0,1]
	v_pk_mul_f32 v[62:63], v[12:13], v[62:63] op_sel_hi:[0,1]
	v_pk_mul_f32 v[64:65], v[12:13], v[104:105] op_sel_hi:[0,1]
	v_pk_fma_f32 v[60:61], v[98:99], v[60:61], v[6:7]
	v_pk_fma_f32 v[14:15], v[0:1], v[14:15], v[4:5]
	v_pk_fma_f32 v[6:7], v[98:99], v[64:65], v[6:7]
	v_pk_fma_f32 v[0:1], v[0:1], v[62:63], v[4:5]
	s_mov_b32 s0, 0x5280000
	v_cvt_pk_bf16_f32 v0, v0, v1
	v_cvt_pk_bf16_f32 v1, v6, v7
	v_add_co_u32_e32 v6, vcc, s0, v58
	v_cvt_pk_bf16_f32 v4, v14, v15
	v_cvt_pk_bf16_f32 v5, v60, v61
	v_addc_co_u32_e32 v7, vcc, 0, v59, vcc
	global_store_dwordx2 v[6:7], v[4:5], off
	v_add_co_u32_e32 v4, vcc, s0, v56
	v_mov_b32_e32 v56, v114
	s_nop 0
	v_addc_co_u32_e32 v5, vcc, 0, v57, vcc
	global_store_dwordx2 v[4:5], v[0:1], off
	v_mov_b32_e32 v0, v108
	v_mov_b32_e32 v1, v110
	v_mov_b32_e32 v110, v109
	v_mov_b32_e32 v57, v116
	v_mov_b32_e32 v116, v115
	v_pk_mul_f32 v[0:1], v[2:3], v[0:1] op_sel_hi:[0,1]
	v_pk_mul_f32 v[14:15], v[2:3], v[110:111] op_sel_hi:[0,1]
	v_pk_mul_f32 v[56:57], v[12:13], v[56:57] op_sel_hi:[0,1]
	v_pk_mul_f32 v[58:59], v[12:13], v[116:117] op_sel_hi:[0,1]
	s_waitcnt vmcnt(12)
	v_pk_fma_f32 v[14:15], v[30:31], v[14:15], v[34:35]
	v_pk_fma_f32 v[0:1], v[28:29], v[0:1], v[32:33]
	v_pk_fma_f32 v[30:31], v[30:31], v[58:59], v[34:35]
	v_pk_fma_f32 v[28:29], v[28:29], v[56:57], v[32:33]
	v_cvt_pk_bf16_f32 v0, v0, v1
	v_cvt_pk_bf16_f32 v1, v14, v15
	v_cvt_pk_bf16_f32 v14, v28, v29
	v_cvt_pk_bf16_f32 v15, v30, v31
	global_store_dwordx2 v[6:7], v[0:1], off offset:512
	global_store_dwordx2 v[4:5], v[14:15], off offset:512
	v_pk_mul_f32 v[0:1], v[76:77], v[2:3] op_sel_hi:[1,0]
	v_pk_mul_f32 v[14:15], v[122:123], v[2:3] op_sel_hi:[1,0]
	s_waitcnt vmcnt(13)
	v_pk_fma_f32 v[0:1], v[24:25], v[0:1], v[16:17]
	v_pk_fma_f32 v[14:15], v[26:27], v[14:15], v[18:19]
	v_pk_mul_f32 v[28:29], v[74:75], v[12:13] op_sel_hi:[1,0]
	v_pk_mul_f32 v[30:31], v[142:143], v[12:13] op_sel_hi:[1,0]
	v_pk_fma_f32 v[16:17], v[24:25], v[28:29], v[16:17]
	v_pk_fma_f32 v[18:19], v[26:27], v[30:31], v[18:19]
	v_cvt_pk_bf16_f32 v0, v0, v1
	v_cvt_pk_bf16_f32 v1, v14, v15
	s_mov_b64 s[0:1], 0x800000
	v_cvt_pk_bf16_f32 v14, v16, v17
	v_cvt_pk_bf16_f32 v15, v18, v19
	global_store_dwordx2 v[6:7], v[0:1], off offset:1024
	global_store_dwordx2 v[4:5], v[14:15], off offset:1024
	v_pk_mul_f32 v[0:1], v[72:73], v[2:3] op_sel_hi:[1,0]
	v_pk_mul_f32 v[2:3], v[70:71], v[2:3] op_sel_hi:[1,0]
	v_lshl_add_u64 v[46:47], v[46:47], 0, s[0:1]
	v_lshl_add_u64 v[50:51], v[50:51], 0, s[0:1]
	s_mov_b32 s0, 0x8fff
	s_waitcnt vmcnt(14)
	v_pk_fma_f32 v[2:3], v[10:11], v[2:3], v[22:23]
	v_pk_fma_f32 v[0:1], v[8:9], v[0:1], v[20:21]
	v_pk_mul_f32 v[14:15], v[68:69], v[12:13] op_sel_hi:[1,0]
	v_pk_mul_f32 v[12:13], v[66:67], v[12:13] op_sel_hi:[1,0]
	s_mov_b64 s[4:5], 0x1000000
	v_cmp_lt_i32_e32 vcc, s0, v152
	v_pk_fma_f32 v[10:11], v[10:11], v[12:13], v[22:23]
	v_pk_fma_f32 v[8:9], v[8:9], v[14:15], v[20:21]
	v_cvt_pk_bf16_f32 v0, v0, v1
	v_cvt_pk_bf16_f32 v1, v2, v3
	v_lshl_add_u64 v[48:49], v[48:49], 0, s[4:5]
	s_or_b64 s[16:17], vcc, s[16:17]
	v_lshl_add_u64 v[52:53], v[52:53], 0, s[4:5]
	v_cvt_pk_bf16_f32 v2, v8, v9
	v_cvt_pk_bf16_f32 v3, v10, v11
	global_store_dwordx2 v[6:7], v[0:1], off offset:1536
	global_store_dwordx2 v[4:5], v[2:3], off offset:1536
	s_andn2_b64 exec, exec, s[16:17]
	s_cbranch_execz .LBB0_390

.LBB0_427:
	s_or_b64 exec, exec, s[6:7]
	v_lshrrev_b32_e32 v36, 12, v40
	v_readlane_b32 s0, v253, 55
	v_add_u32_e32 v36, 1, v36
	v_readlane_b32 s1, v253, 56
	v_cndmask_b32_e64 v38, v36, 0, s[4:5]
	s_waitcnt vmcnt(7)
	v_lshlrev_b32_e32 v148, 16, v146
	v_mov_b64_e32 v[36:37], s[0:1]
	s_mov_b32 s0, 0x9000
	v_mad_u64_u32 v[36:37], s[0:1], v38, s0, v[36:37]
	v_lshl_add_u64 v[110:111], v[36:37], 0, v[130:131]
	s_mov_b64 s[0:1], 0x2000
	v_add_co_u32_e32 v54, vcc, 0x2000, v110
	v_lshl_add_u64 v[52:53], v[110:111], 0, s[0:1]
	s_nop 0
	v_addc_co_u32_e32 v55, vcc, 0, v111, vcc
	global_load_dwordx4 v[36:39], v[86:87], off
	global_load_dwordx4 v[40:43], v[86:87], off offset:1024
	global_load_dwordx4 v[44:47], v[52:53], off offset:1024
	global_load_dwordx4 v[48:51], v[52:53], off offset:2048
	global_load_dwordx4 v[64:67], v[54:55], off
	global_load_dwordx4 v[56:59], v[52:53], off offset:3072
	global_load_dwordx4 v[68:71], v[86:87], off offset:2048
	global_load_dwordx4 v[60:63], v[86:87], off offset:3072
	v_and_b32_e32 v149, 0xffff0000, v146
	s_waitcnt vmcnt(14)
	v_lshlrev_b32_e32 v170, 16, v154
	v_and_b32_e32 v171, 0xffff0000, v154
	v_lshlrev_b32_e32 v146, 16, v147
	v_and_b32_e32 v147, 0xffff0000, v147
	v_lshlrev_b32_e32 v154, 16, v155
	v_and_b32_e32 v155, 0xffff0000, v155
	v_pk_add_f32 v[148:149], v[148:149], v[170:171]
	v_pk_add_f32 v[146:147], v[146:147], v[154:155]
	v_lshlrev_b32_e32 v154, 16, v116
	v_and_b32_e32 v155, 0xffff0000, v116
	v_lshlrev_b32_e32 v170, 16, v120
	v_and_b32_e32 v171, 0xffff0000, v120
	v_pk_add_f32 v[154:155], v[154:155], v[170:171]
	v_lshlrev_b32_e32 v116, 16, v117
	v_and_b32_e32 v117, 0xffff0000, v117
	v_lshlrev_b32_e32 v120, 16, v121
	v_and_b32_e32 v121, 0xffff0000, v121
	v_mov_b32_e32 v170, v149
	v_mov_b32_e32 v171, v147
	v_pk_add_f32 v[116:117], v[116:117], v[120:121]
	v_mov_b32_e32 v120, v148
	v_mov_b32_e32 v121, v146
	v_pk_mul_f32 v[170:171], v[170:171], v[170:171]
	s_movk_i32 s0, 0x4000
	v_pk_fma_f32 v[120:121], v[120:121], v[120:121], v[170:171]
	v_mov_b32_e32 v178, v155
	v_mov_b32_e32 v179, v117
	v_add_co_u32_e32 v156, vcc, s0, v110
	v_pk_add_f32 v[170:171], v[120:121], v[120:121] op_sel:[0,1] op_sel_hi:[1,0]
	v_mov_b32_e32 v120, v154
	v_mov_b32_e32 v121, v116
	v_pk_mul_f32 v[178:179], v[178:179], v[178:179]
	v_addc_co_u32_e32 v157, vcc, 0, v111, vcc
	global_load_dwordx4 v[52:55], v[88:89], off
	global_load_dwordx4 v[72:75], v[156:157], off
	v_pk_fma_f32 v[120:121], v[120:121], v[120:121], v[178:179]
	s_waitcnt vmcnt(14)
	v_lshlrev_b32_e32 v186, 16, v152
	v_pk_add_f32 v[178:179], v[120:121], v[120:121] op_sel:[0,1] op_sel_hi:[1,0]
	v_lshlrev_b32_e32 v120, 16, v150
	v_and_b32_e32 v121, 0xffff0000, v150
	v_and_b32_e32 v187, 0xffff0000, v152
	v_lshlrev_b32_e32 v150, 16, v151
	v_and_b32_e32 v151, 0xffff0000, v151
	v_lshlrev_b32_e32 v152, 16, v153
	v_and_b32_e32 v153, 0xffff0000, v153
	v_pk_add_f32 v[120:121], v[120:121], v[186:187]
	v_pk_add_f32 v[150:151], v[150:151], v[152:153]
	v_lshlrev_b32_e32 v152, 16, v122
	v_and_b32_e32 v153, 0xffff0000, v122
	v_lshlrev_b32_e32 v186, 16, v118
	v_and_b32_e32 v187, 0xffff0000, v118
	v_lshlrev_b32_e32 v122, 16, v123
	v_and_b32_e32 v123, 0xffff0000, v123
	v_lshlrev_b32_e32 v118, 16, v119
	v_and_b32_e32 v119, 0xffff0000, v119
	v_pk_add_f32 v[152:153], v[152:153], v[186:187]
	v_pk_add_f32 v[118:119], v[122:123], v[118:119]
	v_mov_b32_e32 v186, v121
	v_mov_b32_e32 v187, v151
	v_mov_b32_e32 v122, v120
	v_mov_b32_e32 v123, v150
	v_pk_mul_f32 v[186:187], v[186:187], v[186:187]
	v_mov_b32_e32 v188, v153
	v_mov_b32_e32 v189, v119
	v_pk_fma_f32 v[122:123], v[122:123], v[122:123], v[186:187]
	v_mov_b32_e32 v186, v152
	v_mov_b32_e32 v187, v118
	v_pk_mul_f32 v[188:189], v[188:189], v[188:189]
	s_waitcnt vmcnt(12)
	v_lshlrev_b32_e32 v190, 16, v144
	v_pk_fma_f32 v[186:187], v[186:187], v[186:187], v[188:189]
	v_lshlrev_b32_e32 v188, 16, v142
	v_and_b32_e32 v189, 0xffff0000, v142
	v_and_b32_e32 v191, 0xffff0000, v144
	v_lshlrev_b32_e32 v142, 16, v143
	v_and_b32_e32 v143, 0xffff0000, v143
	v_lshlrev_b32_e32 v144, 16, v145
	v_and_b32_e32 v145, 0xffff0000, v145
	v_pk_add_f32 v[188:189], v[188:189], v[190:191]
	v_pk_add_f32 v[142:143], v[142:143], v[144:145]
	v_lshlrev_b32_e32 v144, 16, v114
	v_and_b32_e32 v145, 0xffff0000, v114
	v_lshlrev_b32_e32 v190, 16, v112
	v_and_b32_e32 v191, 0xffff0000, v112
	v_lshlrev_b32_e32 v114, 16, v115
	v_and_b32_e32 v115, 0xffff0000, v115
	v_lshlrev_b32_e32 v112, 16, v113
	v_and_b32_e32 v113, 0xffff0000, v113
	s_waitcnt vmcnt(11)
	v_lshlrev_b32_e32 v196, 16, v124
	v_and_b32_e32 v197, 0xffff0000, v124
	s_waitcnt vmcnt(10)
	v_lshlrev_b32_e32 v198, 16, v126
	v_and_b32_e32 v199, 0xffff0000, v126
	v_lshlrev_b32_e32 v124, 16, v125
	v_and_b32_e32 v125, 0xffff0000, v125
	v_lshlrev_b32_e32 v126, 16, v127
	v_and_b32_e32 v127, 0xffff0000, v127
	v_pk_add_f32 v[112:113], v[114:115], v[112:113]
	v_mul_f32_e32 v114, v189, v189
	v_mul_f32_e32 v130, v143, v143
	v_pk_add_f32 v[196:197], v[196:197], v[198:199]
	v_pk_add_f32 v[124:125], v[124:125], v[126:127]
	v_lshlrev_b32_e32 v126, 16, v34
	v_and_b32_e32 v127, 0xffff0000, v34
	v_lshlrev_b32_e32 v198, 16, v32
	v_and_b32_e32 v199, 0xffff0000, v32
	v_lshlrev_b32_e32 v34, 16, v35
	v_and_b32_e32 v35, 0xffff0000, v35
	v_lshlrev_b32_e32 v32, 16, v33
	v_and_b32_e32 v33, 0xffff0000, v33
	v_pk_add_f32 v[122:123], v[122:123], v[122:123] op_sel:[0,1] op_sel_hi:[1,0]
	v_pk_add_f32 v[144:145], v[144:145], v[190:191]
	v_pk_fma_f32 v[114:115], v[188:189], v[188:189], v[114:115] op_sel_hi:[1,1,0]
	v_pk_fma_f32 v[190:191], v[142:143], v[142:143], v[130:131] op_sel_hi:[1,1,0]
	v_pk_add_f32 v[126:127], v[126:127], v[198:199]
	v_pk_add_f32 v[198:199], v[34:35], v[32:33]
	v_pk_mul_f32 v[32:33], v[196:197], v[196:197]
	v_pk_mul_f32 v[34:35], v[124:125], v[124:125]
	v_mul_f32_e32 v130, v145, v145
	v_mov_b32_e32 v171, v32
	v_mov_b32_e32 v123, v33
	v_mov_b32_e32 v115, v34
	v_mov_b32_e32 v191, v35
	v_pk_fma_f32 v[192:193], v[144:145], v[144:145], v[130:131] op_sel_hi:[1,1,0]
	v_mul_f32_e32 v130, v113, v113
	v_pk_add_f32 v[32:33], v[170:171], v[122:123]
	v_pk_add_f32 v[34:35], v[114:115], v[190:191]
	v_pk_add_f32 v[186:187], v[186:187], v[186:187] op_sel:[0,1] op_sel_hi:[1,0]
	v_pk_fma_f32 v[194:195], v[112:113], v[112:113], v[130:131] op_sel_hi:[1,1,0]
	v_pk_add_f32 v[32:33], v[32:33], v[34:35]
	v_pk_mul_f32 v[34:35], v[126:127], v[126:127]
	v_pk_mul_f32 v[114:115], v[198:199], v[198:199]
	v_mov_b32_e32 v179, v34
	v_mov_b32_e32 v187, v35
	v_mov_b32_e32 v193, v114
	v_mov_b32_e32 v195, v115
	v_pk_add_f32 v[34:35], v[178:179], v[186:187]
	v_pk_add_f32 v[114:115], v[192:193], v[194:195]
	s_mov_b64 s[0:1], 0x3000
	v_pk_add_f32 v[34:35], v[34:35], v[114:115]
	v_mov_b32_e32 v115, v32
	v_mov_b32_e32 v114, v34
	v_mov_b32_e32 v32, v35
	v_pk_add_f32 v[114:115], v[114:115], v[32:33]
	v_mov_b32_e32 v240, v114
	v_mov_b32_e32 v241, v115
	s_nop 1
	v_add_f32_dpp v240, v240, v240 quad_perm:[1,0,3,2] row_mask:0xf bank_mask:0xf
	v_add_f32_dpp v241, v241, v241 quad_perm:[1,0,3,2] row_mask:0xf bank_mask:0xf
	s_nop 0
	v_add_f32_dpp v240, v240, v240 quad_perm:[2,3,0,1] row_mask:0xf bank_mask:0xf
	v_add_f32_dpp v241, v241, v241 quad_perm:[2,3,0,1] row_mask:0xf bank_mask:0xf
	s_nop 0
	v_add_f32_dpp v240, v240, v240 row_half_mirror row_mask:0xf bank_mask:0xf
	v_add_f32_dpp v241, v241, v241 row_half_mirror row_mask:0xf bank_mask:0xf
	s_nop 0
	v_add_f32_dpp v240, v240, v240 row_mirror row_mask:0xf bank_mask:0xf
	v_add_f32_dpp v241, v241, v241 row_mirror row_mask:0xf bank_mask:0xf
	v_mov_b32_e32 v242, v240
	v_mov_b32_e32 v243, v241
	s_nop 1
	v_permlane16_swap_b32_e32 v240, v242
	v_permlane16_swap_b32_e32 v241, v243
	v_add_f32_e32 v240, v240, v242
	v_add_f32_e32 v241, v241, v243
	v_mov_b32_e32 v242, v240
	v_mov_b32_e32 v243, v241
	s_nop 1
	v_permlane32_swap_b32_e32 v240, v242
	v_permlane32_swap_b32_e32 v241, v243
	v_add_f32_e32 v240, v240, v242
	v_add_f32_e32 v241, v241, v243
	global_load_dwordx4 v[32:35], v[156:157], off offset:-4096
	s_waitcnt vmcnt(6)
	v_pk_mul_f32 v[156:157], v[66:67], v[38:39]
	s_waitcnt vmcnt(4)
	v_pk_mul_f32 v[178:179], v[50:51], v[70:71]
	v_lshl_add_u64 v[70:71], v[110:111], 0, s[0:1]
	v_pk_mul_f32 v[114:115], v[64:65], v[36:37]
	s_mov_b64 s[0:1], 0x4000
	v_pk_mul_f32 v[122:123], v[46:47], v[42:43]
	v_pk_mul_f32 v[170:171], v[44:45], v[40:41]
	v_pk_mul_f32 v[186:187], v[48:49], v[68:69]
	s_waitcnt vmcnt(3)
	v_pk_mul_f32 v[190:191], v[58:59], v[62:63]
	v_pk_mul_f32 v[192:193], v[56:57], v[60:61]
	v_lshl_add_u64 v[68:69], v[110:111], 0, s[0:1]
	global_load_dwordx4 v[44:47], v[88:89], off offset:1024
	s_waitcnt vmcnt(2)
	v_pk_add_f32 v[42:43], v[72:73], 1.0 op_sel_hi:[1,0]
	v_pk_add_f32 v[40:41], v[74:75], 1.0 op_sel_hi:[1,0]
	v_pk_mul_f32 v[66:67], v[52:53], v[42:43]
	global_load_dwordx4 v[36:39], v[70:71], off offset:1024
	global_load_dwordx4 v[60:63], v[68:69], off offset:1024
	v_pk_mul_f32 v[64:65], v[54:55], v[40:41]
	s_mov_b32 s0, 0x358637bd
	s_mov_b32 s6, 0x3a800000
	s_add_u32 s28, s28, 0x1000
	global_load_dwordx4 v[48:51], v[88:89], off offset:2048
	global_load_dwordx4 v[40:43], v[88:89], off offset:3072
	global_load_dwordx4 v[56:59], v[68:69], off offset:2048
	global_load_dwordx4 v[52:55], v[68:69], off offset:3072
	v_mov_b64_e32 v[68:69], s[0:1]
	s_mov_b32 s0, 0x800000
	s_addc_u32 s29, s29, 0
	v_mov_b32_e32 v72, v240
	v_mov_b32_e32 v73, v241
	s_waitcnt vmcnt(4)
	v_pk_add_f32 v[62:63], v[62:63], 1.0 op_sel_hi:[1,0]
	v_pk_fma_f32 v[72:73], v[72:73], s[6:7], v[68:69] op_sel_hi:[1,0,0]
	v_pk_mul_f32 v[46:47], v[46:47], v[62:63]
	v_mul_f32_e32 v74, 0x4b800000, v73
	v_cmp_gt_f32_e32 vcc, s0, v73
	v_cmp_gt_f32_e64 s[4:5], s0, v72
	v_pk_add_f32 v[60:61], v[60:61], 1.0 op_sel_hi:[1,0]
	v_cndmask_b32_e32 v73, v73, v74, vcc
	v_mul_f32_e32 v74, 0x4b800000, v72
	v_rsq_f32_e32 v73, v73
	v_cndmask_b32_e64 v72, v72, v74, s[4:5]
	v_rsq_f32_e32 v74, v72
	v_pk_mul_f32 v[44:45], v[44:45], v[60:61]
	v_mul_f32_e32 v72, 0x45800000, v73
	v_cndmask_b32_e32 v72, v73, v72, vcc
	v_mul_f32_e32 v73, 0x45800000, v74
	v_mul_f32_e32 v72, 0.5, v72
	v_cndmask_b32_e64 v73, v74, v73, s[4:5]
	v_mul_f32_e32 v74, 0.5, v73
	v_pk_mul_f32 v[110:111], v[148:149], v[72:73] op_sel_hi:[1,0]
	v_pk_mul_f32 v[146:147], v[146:147], v[72:73] op_sel_hi:[1,0]
	v_pk_fma_f32 v[28:29], v[114:115], v[110:111], v[28:29]
	v_pk_mul_f32 v[110:111], v[154:155], v[74:75] op_sel_hi:[1,0]
	v_pk_fma_f32 v[30:31], v[156:157], v[146:147], v[30:31]
	v_pk_fma_f32 v[24:25], v[114:115], v[110:111], v[24:25]
	v_pk_mul_f32 v[110:111], v[120:121], v[72:73] op_sel_hi:[1,0]
	v_pk_mul_f32 v[114:115], v[150:151], v[72:73] op_sel_hi:[1,0]
	v_pk_fma_f32 v[20:21], v[170:171], v[110:111], v[20:21]
	v_pk_mul_f32 v[110:111], v[152:153], v[74:75] op_sel_hi:[1,0]
	v_pk_mul_f32 v[116:117], v[116:117], v[74:75] op_sel_hi:[1,0]
	v_pk_fma_f32 v[16:17], v[170:171], v[110:111], v[16:17]
	v_pk_mul_f32 v[110:111], v[188:189], v[72:73] op_sel_hi:[1,0]
	v_pk_fma_f32 v[22:23], v[122:123], v[114:115], v[22:23]
	v_pk_mul_f32 v[114:115], v[118:119], v[74:75] op_sel_hi:[1,0]
	v_pk_fma_f32 v[12:13], v[186:187], v[110:111], v[12:13]
	v_pk_mul_f32 v[110:111], v[144:145], v[74:75] op_sel_hi:[1,0]
	v_pk_mul_f32 v[112:113], v[112:113], v[74:75] op_sel_hi:[1,0]
	v_cvt_pk_bf16_f32 v28, v28, v29
	v_cvt_pk_bf16_f32 v29, v30, v31
	v_pk_fma_f32 v[26:27], v[156:157], v[116:117], v[26:27]
	v_pk_fma_f32 v[18:19], v[122:123], v[114:115], v[18:19]
	v_pk_mul_f32 v[114:115], v[142:143], v[72:73] op_sel_hi:[1,0]
	v_pk_fma_f32 v[10:11], v[178:179], v[112:113], v[10:11]
	v_pk_fma_f32 v[8:9], v[186:187], v[110:111], v[8:9]
	v_pk_mul_f32 v[110:111], v[196:197], v[72:73] op_sel_hi:[1,0]
	v_pk_mul_f32 v[72:73], v[124:125], v[72:73] op_sel_hi:[1,0]
	v_and_b32_e32 v113, 0xffff0000, v29
	v_and_b32_e32 v112, 0xffff0000, v28
	v_pk_fma_f32 v[14:15], v[178:179], v[114:115], v[14:15]
	v_pk_fma_f32 v[6:7], v[190:191], v[72:73], v[6:7]
	v_pk_fma_f32 v[4:5], v[192:193], v[110:111], v[4:5]
	v_pk_mul_f32 v[72:73], v[126:127], v[74:75] op_sel_hi:[1,0]
	v_cvt_pk_bf16_f32 v24, v24, v25
	v_cvt_pk_bf16_f32 v25, v26, v27
	v_cvt_pk_bf16_f32 v20, v20, v21
	v_cvt_pk_bf16_f32 v21, v22, v23
	v_cvt_pk_bf16_f32 v26, v12, v13
	v_lshlrev_b32_e32 v111, 16, v29
	v_lshlrev_b32_e32 v110, 16, v28
	v_pk_mul_f32 v[12:13], v[112:113], v[112:113]
	v_pk_fma_f32 v[0:1], v[192:193], v[72:73], v[0:1]
	v_cvt_pk_bf16_f32 v27, v14, v15
	v_cvt_pk_bf16_f32 v72, v4, v5
	v_pk_fma_f32 v[12:13], v[110:111], v[110:111], v[12:13]
	v_and_b32_e32 v121, 0xffff0000, v21
	v_and_b32_e32 v120, 0xffff0000, v20
	v_cvt_pk_bf16_f32 v22, v16, v17
	v_cvt_pk_bf16_f32 v31, v10, v11
	v_lshlrev_b32_e32 v10, 16, v26
	v_and_b32_e32 v11, 0xffff0000, v26
	v_cvt_pk_bf16_f32 v73, v6, v7
	v_lshlrev_b32_e32 v6, 16, v72
	v_pk_add_f32 v[12:13], v[12:13], v[12:13] op_sel_hi:[0,1]
	v_lshlrev_b32_e32 v119, 16, v21
	v_lshlrev_b32_e32 v118, 16, v20
	v_pk_mul_f32 v[16:17], v[120:121], v[120:121]
	v_lshlrev_b32_e32 v142, 16, v27
	v_pk_mul_f32 v[74:75], v[198:199], v[74:75] op_sel_hi:[1,0]
	v_cvt_pk_bf16_f32 v23, v18, v19
	v_pk_fma_f32 v[16:17], v[118:119], v[118:119], v[16:17]
	v_mul_f32_e32 v7, v10, v10
	v_mul_f32_e32 v127, v11, v11
	v_and_b32_e32 v143, 0xffff0000, v27
	v_mul_f32_e32 v12, v142, v142
	v_lshlrev_b32_e32 v148, 16, v31
	v_mov_b32_e32 v126, v6
	v_pk_fma_f32 v[2:3], v[190:191], v[74:75], v[2:3]
	v_cvt_pk_bf16_f32 v30, v8, v9
	v_cvt_pk_bf16_f32 v74, v0, v1
	v_and_b32_e32 v130, 0xffff0000, v72
	v_lshlrev_b32_e32 v4, 16, v73
	v_and_b32_e32 v5, 0xffff0000, v73
	v_and_b32_e32 v117, 0xffff0000, v25
	v_and_b32_e32 v116, 0xffff0000, v24
	v_pk_add_f32 v[16:17], v[16:17], v[16:17] op_sel_hi:[0,1]
	v_and_b32_e32 v125, 0xffff0000, v23
	v_and_b32_e32 v124, 0xffff0000, v22
	v_pk_fma_f32 v[144:145], v[142:143], v[142:143], v[12:13] op_sel_hi:[1,1,0]
	v_and_b32_e32 v149, 0xffff0000, v31
	v_mul_f32_e32 v12, v148, v148
	v_pk_add_f32 v[126:127], v[6:7], v[126:127]
	v_lshlrev_b32_e32 v8, 16, v30
	v_and_b32_e32 v9, 0xffff0000, v30
	v_cvt_pk_bf16_f32 v75, v2, v3
	v_lshlrev_b32_e32 v2, 16, v74
	v_lshlrev_b32_e32 v115, 16, v25
	v_lshlrev_b32_e32 v114, 16, v24
	v_pk_mul_f32 v[14:15], v[116:117], v[116:117]
	v_lshlrev_b32_e32 v123, 16, v23
	v_lshlrev_b32_e32 v122, 16, v22
	v_pk_mul_f32 v[18:19], v[124:125], v[124:125]
	v_pk_fma_f32 v[150:151], v[148:149], v[148:149], v[12:13] op_sel_hi:[1,1,0]
	v_mul_f32_e32 v144, v130, v130
	v_mul_f32_e32 v12, v4, v4
	v_mul_f32_e32 v16, v5, v5
	v_mul_f32_e32 v152, v6, v6
	v_mov_b32_e32 v153, v127
	v_pk_fma_f32 v[14:15], v[114:115], v[114:115], v[14:15]
	v_pk_fma_f32 v[18:19], v[122:123], v[122:123], v[18:19]
	v_mul_f32_e32 v3, v8, v8
	v_mul_f32_e32 v147, v9, v9
	v_pk_add_f32 v[126:127], v[152:153], v[144:145]
	v_pk_add_f32 v[12:13], v[12:13], v[16:17]
	v_mov_b32_e32 v146, v2
	v_and_b32_e32 v154, 0xffff0000, v74
	v_lshlrev_b32_e32 v0, 16, v75
	v_and_b32_e32 v1, 0xffff0000, v75
	v_pk_add_f32 v[14:15], v[14:15], v[14:15] op_sel_hi:[0,1]
	v_pk_add_f32 v[18:19], v[18:19], v[18:19] op_sel_hi:[0,1]
	v_pk_add_f32 v[12:13], v[126:127], v[12:13]
	v_pk_add_f32 v[126:127], v[2:3], v[146:147]
	v_mul_f32_e32 v150, v154, v154
	v_mul_f32_e32 v14, v0, v0
	v_mul_f32_e32 v18, v1, v1
	v_mul_f32_e32 v16, v2, v2
	v_mov_b32_e32 v17, v127
	v_pk_add_f32 v[16:17], v[16:17], v[150:151]
	v_pk_add_f32 v[14:15], v[14:15], v[18:19]
	s_waitcnt vmcnt(1)
	v_pk_add_f32 v[56:57], v[56:57], 1.0 op_sel_hi:[1,0]
	v_pk_add_f32 v[14:15], v[16:17], v[14:15]
	v_mov_b32_e32 v17, v12
	v_mov_b32_e32 v16, v14
	v_mov_b32_e32 v12, v15
	v_pk_add_f32 v[16:17], v[16:17], v[12:13]
	v_mov_b32_e32 v240, v16
	v_mov_b32_e32 v241, v17
	s_nop 1
	v_add_f32_dpp v240, v240, v240 quad_perm:[1,0,3,2] row_mask:0xf bank_mask:0xf
	v_add_f32_dpp v241, v241, v241 quad_perm:[1,0,3,2] row_mask:0xf bank_mask:0xf
	s_nop 0
	v_add_f32_dpp v240, v240, v240 quad_perm:[2,3,0,1] row_mask:0xf bank_mask:0xf
	v_add_f32_dpp v241, v241, v241 quad_perm:[2,3,0,1] row_mask:0xf bank_mask:0xf
	s_nop 0
	v_add_f32_dpp v240, v240, v240 row_half_mirror row_mask:0xf bank_mask:0xf
	v_add_f32_dpp v241, v241, v241 row_half_mirror row_mask:0xf bank_mask:0xf
	s_nop 0
	v_add_f32_dpp v240, v240, v240 row_mirror row_mask:0xf bank_mask:0xf
	v_add_f32_dpp v241, v241, v241 row_mirror row_mask:0xf bank_mask:0xf
	v_mov_b32_e32 v242, v240
	v_mov_b32_e32 v243, v241
	s_nop 1
	v_permlane16_swap_b32_e32 v240, v242
	v_permlane16_swap_b32_e32 v241, v243
	v_add_f32_e32 v240, v240, v242
	v_add_f32_e32 v241, v241, v243
	v_mov_b32_e32 v242, v240
	v_mov_b32_e32 v243, v241
	s_nop 1
	v_permlane32_swap_b32_e32 v240, v242
	v_permlane32_swap_b32_e32 v241, v243
	v_add_f32_e32 v240, v240, v242
	v_add_f32_e32 v241, v241, v243
	global_load_dwordx4 v[12:15], v[70:71], off offset:3072
	v_pk_add_f32 v[58:59], v[58:59], 1.0 op_sel_hi:[1,0]
	v_pk_mul_f32 v[48:49], v[48:49], v[56:57]
	v_pk_mul_f32 v[50:51], v[50:51], v[58:59]
	global_load_dwordx4 v[16:19], v[70:71], off offset:2048
	s_waitcnt vmcnt(2)
	v_pk_add_f32 v[54:55], v[54:55], 1.0 op_sel_hi:[1,0]
	v_pk_add_f32 v[52:53], v[52:53], 1.0 op_sel_hi:[1,0]
	v_pk_mul_f32 v[42:43], v[42:43], v[54:55]
	v_pk_mul_f32 v[40:41], v[40:41], v[52:53]
	v_lshlrev_b64 v[52:53], 12, v[104:105]
	v_lshl_add_u64 v[54:55], v[98:99], 0, v[80:81]
	v_lshl_add_u64 v[52:53], v[92:93], 0, v[52:53]
	global_store_dwordx2 v[54:55], v[28:29], off offset:2048
	global_store_dwordx2 v[52:53], v[24:25], off offset:2048
	global_store_dwordx2 v[54:55], v[20:21], off offset:2560
	global_store_dwordx2 v[52:53], v[22:23], off offset:2560
	global_store_dwordx2 v[54:55], v[26:27], off offset:3072
	global_store_dwordx2 v[52:53], v[30:31], off offset:3072
	global_store_dwordx2 v[54:55], v[72:73], off offset:3584
	v_mov_b32_e32 v26, v110
	v_mov_b32_e32 v27, v112
	v_mov_b32_e32 v112, v111
	v_mov_b32_e32 v30, v114
	v_mov_b32_e32 v31, v116
	v_mov_b32_e32 v116, v115
	global_store_dwordx2 v[52:53], v[74:75], off offset:3584
	v_mov_b32_e32 v20, v240
	v_mov_b32_e32 v21, v241
	s_nop 0
	v_pk_fma_f32 v[20:21], v[20:21], s[6:7], v[68:69] op_sel_hi:[1,0,0]
	v_lshl_add_u64 v[24:25], v[90:91], 0, v[108:109]
	v_mul_f32_e32 v3, 0x4b800000, v21
	v_cmp_gt_f32_e32 vcc, s0, v21
	v_mul_f32_e32 v7, 0x4b800000, v20
	v_cmp_gt_f32_e64 s[4:5], s0, v20
	v_cndmask_b32_e32 v3, v21, v3, vcc
	v_rsq_f32_e32 v3, v3
	v_cndmask_b32_e64 v7, v20, v7, s[4:5]
	v_rsq_f32_e32 v7, v7
	s_mov_b32 s0, 0x5280000
	v_mul_f32_e32 v20, 0x45800000, v3
	v_cndmask_b32_e32 v20, v3, v20, vcc
	v_mul_f32_e32 v3, 0x45800000, v7
	v_cndmask_b32_e64 v22, v7, v3, s[4:5]
	v_pk_mul_f32 v[26:27], v[20:21], v[26:27] op_sel_hi:[0,1]
	v_pk_mul_f32 v[28:29], v[20:21], v[112:113] op_sel_hi:[0,1]
	v_pk_mul_f32 v[30:31], v[22:23], v[30:31] op_sel_hi:[0,1]
	v_pk_fma_f32 v[28:29], v[64:65], v[28:29], v[34:35]
	v_pk_fma_f32 v[26:27], v[66:67], v[26:27], v[32:33]
	v_pk_fma_f32 v[30:31], v[66:67], v[30:31], v[32:33]
	v_pk_mul_f32 v[52:53], v[22:23], v[116:117] op_sel_hi:[0,1]
	v_cvt_pk_bf16_f32 v26, v26, v27
	v_cvt_pk_bf16_f32 v27, v28, v29
	v_cvt_pk_bf16_f32 v28, v30, v31
	v_add_co_u32_e32 v30, vcc, s0, v106
	v_pk_fma_f32 v[34:35], v[64:65], v[52:53], v[34:35]
	s_nop 0
	v_addc_co_u32_e32 v31, vcc, 0, v107, vcc
	v_cvt_pk_bf16_f32 v29, v34, v35
	global_store_dwordx2 v[30:31], v[26:27], off
	global_store_dwordx2 v[24:25], v[28:29], off
	v_mov_b32_e32 v26, v118
	v_mov_b32_e32 v27, v120
	v_mov_b32_e32 v120, v119
	v_mov_b32_e32 v3, v154
	v_pk_mul_f32 v[26:27], v[20:21], v[26:27] op_sel_hi:[0,1]
	v_pk_mul_f32 v[28:29], v[20:21], v[120:121] op_sel_hi:[0,1]
	v_mov_b32_e32 v32, v122
	v_mov_b32_e32 v33, v124
	v_mov_b32_e32 v124, v123
	v_pk_mul_f32 v[2:3], v[2:3], v[22:23] op_sel_hi:[1,0]
	v_pk_mul_f32 v[0:1], v[0:1], v[22:23] op_sel_hi:[1,0]
	v_pk_fma_f32 v[28:29], v[46:47], v[28:29], v[38:39]
	v_pk_fma_f32 v[26:27], v[44:45], v[26:27], v[36:37]
	v_pk_mul_f32 v[32:33], v[22:23], v[32:33] op_sel_hi:[0,1]
	v_pk_mul_f32 v[34:35], v[22:23], v[124:125] op_sel_hi:[0,1]
	s_waitcnt vmcnt(11)
	v_pk_fma_f32 v[0:1], v[42:43], v[0:1], v[14:15]
	v_pk_fma_f32 v[2:3], v[40:41], v[2:3], v[12:13]
	v_pk_fma_f32 v[34:35], v[46:47], v[34:35], v[38:39]
	v_pk_fma_f32 v[32:33], v[44:45], v[32:33], v[36:37]
	v_cvt_pk_bf16_f32 v26, v26, v27
	v_cvt_pk_bf16_f32 v27, v28, v29
	v_mov_b32_e32 v7, v130
	v_cvt_pk_bf16_f32 v2, v2, v3
	v_cvt_pk_bf16_f32 v3, v0, v1
	v_add_u32_e32 v0, s28, v76
	s_mov_b64 s[0:1], 0x800000
	v_cvt_pk_bf16_f32 v28, v32, v33
	v_cvt_pk_bf16_f32 v29, v34, v35
	global_store_dwordx2 v[30:31], v[26:27], off offset:512
	global_store_dwordx2 v[24:25], v[28:29], off offset:512
	v_pk_mul_f32 v[10:11], v[10:11], v[20:21] op_sel_hi:[1,0]
	v_pk_mul_f32 v[26:27], v[142:143], v[20:21] op_sel_hi:[1,0]
	v_pk_mul_f32 v[6:7], v[6:7], v[20:21] op_sel_hi:[1,0]
	v_pk_mul_f32 v[4:5], v[4:5], v[20:21] op_sel_hi:[1,0]
	v_add_u32_e32 v0, 0xfffff000, v0
	v_lshl_add_u64 v[96:97], v[96:97], 0, s[0:1]
	s_mov_b32 s0, 0x8fff
	s_waitcnt vmcnt(12)
	v_pk_fma_f32 v[26:27], v[50:51], v[26:27], v[18:19]
	v_pk_fma_f32 v[10:11], v[48:49], v[10:11], v[16:17]
	v_pk_mul_f32 v[8:9], v[8:9], v[22:23] op_sel_hi:[1,0]
	v_pk_mul_f32 v[28:29], v[148:149], v[22:23] op_sel_hi:[1,0]
	v_pk_fma_f32 v[4:5], v[42:43], v[4:5], v[14:15]
	v_pk_fma_f32 v[6:7], v[40:41], v[6:7], v[12:13]
	s_mov_b64 s[4:5], 0x1000000
	v_cmp_lt_i32_e32 vcc, s0, v0
	v_pk_fma_f32 v[18:19], v[50:51], v[28:29], v[18:19]
	v_pk_fma_f32 v[8:9], v[48:49], v[8:9], v[16:17]
	v_cvt_pk_bf16_f32 v10, v10, v11
	v_cvt_pk_bf16_f32 v11, v26, v27
	v_cvt_pk_bf16_f32 v6, v6, v7
	v_cvt_pk_bf16_f32 v7, v4, v5
	v_lshl_add_u64 v[98:99], v[98:99], 0, s[4:5]
	s_or_b64 s[16:17], vcc, s[16:17]
	v_lshl_add_u64 v[102:103], v[102:103], 0, s[4:5]
	v_cvt_pk_bf16_f32 v8, v8, v9
	v_cvt_pk_bf16_f32 v9, v18, v19
	global_store_dwordx2 v[30:31], v[10:11], off offset:1024
	global_store_dwordx2 v[24:25], v[8:9], off offset:1024
	global_store_dwordx2 v[30:31], v[6:7], off offset:1536
	global_store_dwordx2 v[24:25], v[2:3], off offset:1536
	s_andn2_b64 exec, exec, s[16:17]
	s_cbranch_execz .LBB0_448

.LBB0_1359:
	s_or_b64 exec, exec, s[4:5]
	v_add_u32_e32 v12, 0x6000, v130
	v_ashrrev_i32_e32 v12, 12, v12
	s_movk_i32 s0, 0x1fff
	v_add_u32_e32 v12, 1, v12
	v_cmp_lt_i32_e32 vcc, s0, v150
	s_waitcnt vmcnt(13)
	v_lshlrev_b32_e32 v72, 16, v0
	v_and_b32_e32 v73, 0xffff0000, v0
	v_cndmask_b32_e32 v0, 0, v12, vcc
	v_lshlrev_b32_e32 v78, 16, v1
	v_and_b32_e32 v79, 0xffff0000, v1
	v_mul_hi_i32_i24_e32 v1, 0x2400, v0
	v_mul_i32_i24_e32 v0, 0x2400, v0
	v_lshlrev_b64 v[0:1], 2, v[0:1]
	s_waitcnt vmcnt(9)
	v_lshlrev_b32_e32 v70, 16, v2
	v_and_b32_e32 v71, 0xffff0000, v2
	v_lshlrev_b32_e32 v74, 16, v3
	v_and_b32_e32 v75, 0xffff0000, v3
	v_lshl_add_u64 v[2:3], v[40:41], 0, v[0:1]
	v_lshlrev_b32_e32 v90, 16, v8
	v_and_b32_e32 v91, 0xffff0000, v8
	v_lshlrev_b32_e32 v92, 16, v9
	v_and_b32_e32 v93, 0xffff0000, v9
	v_lshlrev_b32_e32 v84, 16, v10
	v_and_b32_e32 v85, 0xffff0000, v10
	v_lshlrev_b32_e32 v88, 16, v11
	v_and_b32_e32 v89, 0xffff0000, v11
	v_lshlrev_b32_e32 v80, 16, v4
	v_and_b32_e32 v81, 0xffff0000, v4
	v_lshlrev_b32_e32 v86, 16, v5
	v_and_b32_e32 v87, 0xffff0000, v5
	v_lshlrev_b32_e32 v76, 16, v6
	v_and_b32_e32 v77, 0xffff0000, v6
	v_lshlrev_b32_e32 v82, 16, v7
	v_and_b32_e32 v83, 0xffff0000, v7
	global_load_dwordx4 v[4:7], v[2:3], off
	global_load_dwordx4 v[8:11], v[2:3], off offset:1024
	global_load_dwordx4 v[20:23], v[42:43], off
	global_load_dwordx4 v[12:15], v[42:43], off offset:1024
	global_load_dwordx4 v[16:19], v[2:3], off offset:2048
	global_load_dwordx4 v[24:27], v[2:3], off offset:3072
	global_load_dwordx4 v[32:35], v[42:43], off offset:2048
	global_load_dwordx4 v[28:31], v[42:43], off offset:3072
	v_lshl_add_u64 v[0:1], s[16:17], 0, v[0:1]
	v_mov_b32_e32 v55, v131
	v_lshl_add_u64 v[64:65], v[0:1], 0, v[54:55]
	s_movk_i32 s0, 0x1000
	v_add_co_u32_e32 v0, vcc, s0, v64
	s_waitcnt vmcnt(15)
	v_lshlrev_b32_e32 v126, 16, v110
	v_addc_co_u32_e32 v1, vcc, 0, v65, vcc
	global_load_dwordx4 v[0:3], v[0:1], off
	v_and_b32_e32 v127, 0xffff0000, v110
	s_waitcnt vmcnt(15)
	v_lshlrev_b32_e32 v142, 16, v118
	v_and_b32_e32 v143, 0xffff0000, v118
	v_lshlrev_b32_e32 v110, 16, v111
	v_and_b32_e32 v111, 0xffff0000, v111
	v_lshlrev_b32_e32 v118, 16, v119
	v_and_b32_e32 v119, 0xffff0000, v119
	v_pk_add_f32 v[126:127], v[126:127], v[142:143]
	v_pk_add_f32 v[110:111], v[110:111], v[118:119]
	v_lshlrev_b32_e32 v118, 16, v94
	v_and_b32_e32 v119, 0xffff0000, v94
	v_lshlrev_b32_e32 v142, 16, v96
	v_and_b32_e32 v143, 0xffff0000, v96
	v_lshlrev_b32_e32 v94, 16, v95
	v_and_b32_e32 v95, 0xffff0000, v95
	v_lshlrev_b32_e32 v96, 16, v97
	v_and_b32_e32 v97, 0xffff0000, v97
	v_pk_add_f32 v[118:119], v[118:119], v[142:143]
	v_pk_add_f32 v[94:95], v[94:95], v[96:97]
	v_mov_b32_e32 v142, v127
	v_mov_b32_e32 v143, v111
	v_mov_b32_e32 v96, v126
	v_mov_b32_e32 v97, v110
	v_pk_mul_f32 v[142:143], v[142:143], v[142:143]
	v_mov_b32_e32 v152, v119
	v_mov_b32_e32 v153, v95
	v_pk_fma_f32 v[96:97], v[96:97], v[96:97], v[142:143]
	v_mov_b32_e32 v142, v118
	v_mov_b32_e32 v143, v94
	v_pk_mul_f32 v[152:153], v[152:153], v[152:153]
	s_waitcnt vmcnt(13)
	v_lshlrev_b32_e32 v154, 16, v122
	v_pk_fma_f32 v[142:143], v[142:143], v[142:143], v[152:153]
	v_and_b32_e32 v155, 0xffff0000, v122
	v_pk_add_f32 v[152:153], v[142:143], v[142:143] op_sel:[0,1] op_sel_hi:[1,0]
	v_lshlrev_b32_e32 v142, 16, v114
	v_and_b32_e32 v143, 0xffff0000, v114
	v_lshlrev_b32_e32 v114, 16, v115
	v_and_b32_e32 v115, 0xffff0000, v115
	v_lshlrev_b32_e32 v122, 16, v123
	v_and_b32_e32 v123, 0xffff0000, v123
	v_pk_add_f32 v[142:143], v[142:143], v[154:155]
	v_pk_add_f32 v[114:115], v[114:115], v[122:123]
	v_lshlrev_b32_e32 v122, 16, v106
	v_and_b32_e32 v123, 0xffff0000, v106
	v_lshlrev_b32_e32 v154, 16, v102
	v_and_b32_e32 v155, 0xffff0000, v102
	v_lshlrev_b32_e32 v106, 16, v107
	v_and_b32_e32 v107, 0xffff0000, v107
	v_lshlrev_b32_e32 v102, 16, v103
	v_and_b32_e32 v103, 0xffff0000, v103
	v_pk_add_f32 v[122:123], v[122:123], v[154:155]
	v_pk_add_f32 v[102:103], v[106:107], v[102:103]
	v_mov_b32_e32 v154, v143
	v_mov_b32_e32 v155, v115
	v_mov_b32_e32 v106, v142
	v_mov_b32_e32 v107, v114
	v_pk_mul_f32 v[154:155], v[154:155], v[154:155]
	v_mov_b32_e32 v156, v123
	v_mov_b32_e32 v157, v103
	v_pk_fma_f32 v[106:107], v[106:107], v[106:107], v[154:155]
	v_mov_b32_e32 v154, v122
	v_mov_b32_e32 v155, v102
	v_pk_mul_f32 v[156:157], v[156:157], v[156:157]
	s_waitcnt vmcnt(11)
	v_lshlrev_b32_e32 v170, 16, v120
	v_pk_fma_f32 v[154:155], v[154:155], v[154:155], v[156:157]
	v_lshlrev_b32_e32 v156, 16, v112
	v_and_b32_e32 v157, 0xffff0000, v112
	v_and_b32_e32 v171, 0xffff0000, v120
	v_lshlrev_b32_e32 v112, 16, v113
	v_and_b32_e32 v113, 0xffff0000, v113
	v_lshlrev_b32_e32 v120, 16, v121
	v_and_b32_e32 v121, 0xffff0000, v121
	v_pk_add_f32 v[156:157], v[156:157], v[170:171]
	v_pk_add_f32 v[112:113], v[112:113], v[120:121]
	v_lshlrev_b32_e32 v120, 16, v100
	v_and_b32_e32 v121, 0xffff0000, v100
	v_lshlrev_b32_e32 v170, 16, v98
	v_and_b32_e32 v171, 0xffff0000, v98
	v_lshlrev_b32_e32 v100, 16, v101
	v_and_b32_e32 v101, 0xffff0000, v101
	v_lshlrev_b32_e32 v98, 16, v99
	v_and_b32_e32 v99, 0xffff0000, v99
	s_waitcnt vmcnt(10)
	v_lshlrev_b32_e32 v184, 16, v116
	v_and_b32_e32 v185, 0xffff0000, v116
	s_waitcnt vmcnt(9)
	v_lshlrev_b32_e32 v186, 16, v124
	v_and_b32_e32 v187, 0xffff0000, v124
	v_lshlrev_b32_e32 v116, 16, v117
	v_and_b32_e32 v117, 0xffff0000, v117
	v_lshlrev_b32_e32 v124, 16, v125
	v_and_b32_e32 v125, 0xffff0000, v125
	v_pk_add_f32 v[120:121], v[120:121], v[170:171]
	v_pk_add_f32 v[98:99], v[100:101], v[98:99]
	v_mul_f32_e32 v100, v157, v157
	v_mul_f32_e32 v170, v113, v113
	v_pk_add_f32 v[184:185], v[184:185], v[186:187]
	v_pk_add_f32 v[116:117], v[116:117], v[124:125]
	v_lshlrev_b32_e32 v124, 16, v108
	v_and_b32_e32 v125, 0xffff0000, v108
	v_lshlrev_b32_e32 v186, 16, v104
	v_and_b32_e32 v187, 0xffff0000, v104
	v_lshlrev_b32_e32 v108, 16, v109
	v_and_b32_e32 v109, 0xffff0000, v109
	v_lshlrev_b32_e32 v104, 16, v105
	v_and_b32_e32 v105, 0xffff0000, v105
	v_pk_add_f32 v[96:97], v[96:97], v[96:97] op_sel:[0,1] op_sel_hi:[1,0]
	v_pk_add_f32 v[106:107], v[106:107], v[106:107] op_sel:[0,1] op_sel_hi:[1,0]
	v_pk_fma_f32 v[100:101], v[156:157], v[156:157], v[100:101] op_sel_hi:[1,1,0]
	v_pk_fma_f32 v[170:171], v[112:113], v[112:113], v[170:171] op_sel_hi:[1,1,0]
	v_pk_add_f32 v[124:125], v[124:125], v[186:187]
	v_pk_add_f32 v[104:105], v[108:109], v[104:105]
	v_pk_mul_f32 v[108:109], v[184:185], v[184:185]
	v_pk_mul_f32 v[186:187], v[116:117], v[116:117]
	v_mov_b32_e32 v97, v108
	v_mov_b32_e32 v107, v109
	v_mov_b32_e32 v101, v186
	v_mov_b32_e32 v171, v187
	v_mul_f32_e32 v178, v121, v121
	v_mul_f32_e32 v182, v99, v99
	v_pk_add_f32 v[96:97], v[96:97], v[106:107]
	v_pk_add_f32 v[100:101], v[100:101], v[170:171]
	v_pk_add_f32 v[154:155], v[154:155], v[154:155] op_sel:[0,1] op_sel_hi:[1,0]
	v_pk_fma_f32 v[178:179], v[120:121], v[120:121], v[178:179] op_sel_hi:[1,1,0]
	v_pk_fma_f32 v[182:183], v[98:99], v[98:99], v[182:183] op_sel_hi:[1,1,0]
	v_pk_add_f32 v[96:97], v[96:97], v[100:101]
	v_pk_mul_f32 v[100:101], v[124:125], v[124:125]
	v_pk_mul_f32 v[106:107], v[104:105], v[104:105]
	v_mov_b32_e32 v153, v100
	v_mov_b32_e32 v155, v101
	v_mov_b32_e32 v179, v106
	v_mov_b32_e32 v183, v107
	v_pk_add_f32 v[100:101], v[152:153], v[154:155]
	v_pk_add_f32 v[106:107], v[178:179], v[182:183]
	s_waitcnt vmcnt(6)
	v_pk_mul_f32 v[154:155], v[4:5], v[20:21]
	v_pk_add_f32 v[100:101], v[100:101], v[106:107]
	v_mov_b32_e32 v107, v96
	v_mov_b32_e32 v106, v100
	v_mov_b32_e32 v96, v101
	v_pk_add_f32 v[96:97], v[106:107], v[96:97]
	v_mov_b32_e32 v240, v96
	v_mov_b32_e32 v241, v97
	s_nop 1
	v_add_f32_dpp v240, v240, v240 quad_perm:[1,0,3,2] row_mask:0xf bank_mask:0xf
	v_add_f32_dpp v241, v241, v241 quad_perm:[1,0,3,2] row_mask:0xf bank_mask:0xf
	s_nop 0
	v_add_f32_dpp v240, v240, v240 quad_perm:[2,3,0,1] row_mask:0xf bank_mask:0xf
	v_add_f32_dpp v241, v241, v241 quad_perm:[2,3,0,1] row_mask:0xf bank_mask:0xf
	s_nop 0
	v_add_f32_dpp v240, v240, v240 row_half_mirror row_mask:0xf bank_mask:0xf
	v_add_f32_dpp v241, v241, v241 row_half_mirror row_mask:0xf bank_mask:0xf
	s_nop 0
	v_add_f32_dpp v240, v240, v240 row_mirror row_mask:0xf bank_mask:0xf
	v_add_f32_dpp v241, v241, v241 row_mirror row_mask:0xf bank_mask:0xf
	v_mov_b32_e32 v242, v240
	v_mov_b32_e32 v243, v241
	s_nop 1
	v_permlane16_swap_b32_e32 v240, v242
	v_permlane16_swap_b32_e32 v241, v243
	v_add_f32_e32 v240, v240, v242
	v_add_f32_e32 v241, v241, v243
	v_mov_b32_e32 v242, v240
	v_mov_b32_e32 v243, v241
	s_nop 1
	v_permlane32_swap_b32_e32 v240, v242
	v_permlane32_swap_b32_e32 v241, v243
	v_add_f32_e32 v240, v240, v242
	v_add_f32_e32 v241, v241, v243
	v_pk_mul_f32 v[152:153], v[6:7], v[22:23]
	s_waitcnt vmcnt(5)
	v_pk_mul_f32 v[178:179], v[8:9], v[12:13]
	v_pk_mul_f32 v[170:171], v[10:11], v[14:15]
	s_mov_b64 s[0:1], 0x1000
	s_waitcnt vmcnt(2)
	v_pk_mul_f32 v[182:183], v[16:17], v[32:33]
	s_waitcnt vmcnt(1)
	v_pk_mul_f32 v[186:187], v[26:27], v[30:31]
	v_pk_mul_f32 v[188:189], v[24:25], v[28:29]
	v_lshl_add_u64 v[16:17], v[64:65], 0, s[0:1]
	s_mov_b32 s0, 0x358637bd
	s_mov_b32 s6, 0x3a800000
	v_lshlrev_b32_e32 v106, 16, v68
	v_and_b32_e32 v107, 0xffff0000, v68
	s_waitcnt vmcnt(0)
	v_pk_add_f32 v[96:97], v[2:3], 1.0 op_sel_hi:[1,0]
	v_pk_mul_f32 v[100:101], v[18:19], v[34:35]
	v_lshlrev_b32_e32 v68, 16, v69
	v_and_b32_e32 v69, 0xffff0000, v69
	global_load_dwordx4 v[4:7], v[64:65], off
	global_load_dwordx4 v[8:11], v[16:17], off offset:3072
	v_lshlrev_b32_e32 v108, 16, v66
	v_and_b32_e32 v109, 0xffff0000, v66
	v_lshlrev_b32_e32 v66, 16, v67
	global_load_dwordx4 v[28:31], v[44:45], off
	global_load_dwordx4 v[20:23], v[44:45], off offset:1024
	global_load_dwordx4 v[24:27], v[16:17], off offset:1024
	global_load_dwordx4 v[12:15], v[16:17], off offset:2048
	v_and_b32_e32 v67, 0xffff0000, v67
	v_pk_add_f32 v[0:1], v[0:1], 1.0 op_sel_hi:[1,0]
	v_add_u32_e32 v130, 0x1000, v130
	v_mov_b32_e32 v16, v240
	v_mov_b32_e32 v17, v241
	v_mov_b64_e32 v[2:3], s[0:1]
	v_pk_fma_f32 v[16:17], v[16:17], s[6:7], v[2:3] op_sel_hi:[1,0,0]
	s_mov_b32 s0, 0x800000
	v_mul_f32_e32 v18, 0x4b800000, v17
	v_cmp_gt_f32_e32 vcc, s0, v17
	v_cmp_gt_f32_e64 s[4:5], s0, v16
	s_waitcnt vmcnt(4)
	v_pk_add_f32 v[10:11], v[10:11], 1.0 op_sel_hi:[1,0]
	v_cndmask_b32_e32 v17, v17, v18, vcc
	v_rsq_f32_e32 v55, v17
	v_mul_f32_e32 v17, 0x4b800000, v16
	v_cndmask_b32_e64 v16, v16, v17, s[4:5]
	v_rsq_f32_e32 v151, v16
	global_load_dwordx4 v[32:35], v[44:45], off offset:2048
	global_load_dwordx4 v[16:19], v[44:45], off offset:3072
	v_mul_f32_e32 v181, 0x45800000, v55
	v_cndmask_b32_e32 v190, v55, v181, vcc
	v_mul_f32_e32 v55, 0x45800000, v151
	v_cndmask_b32_e64 v192, v151, v55, s[4:5]
	v_pk_mul_f32 v[94:95], v[94:95], v[192:193] op_sel_hi:[1,0]
	v_pk_mul_f32 v[98:99], v[98:99], v[192:193] op_sel_hi:[1,0]
	v_pk_fma_f32 v[88:89], v[152:153], v[94:95], v[88:89]
	v_pk_mul_f32 v[94:95], v[142:143], v[190:191] op_sel_hi:[1,0]
	v_pk_mul_f32 v[126:127], v[126:127], v[190:191] op_sel_hi:[1,0]
	v_pk_fma_f32 v[80:81], v[178:179], v[94:95], v[80:81]
	v_pk_mul_f32 v[94:95], v[122:123], v[192:193] op_sel_hi:[1,0]
	v_pk_mul_f32 v[110:111], v[110:111], v[190:191] op_sel_hi:[1,0]
	v_pk_fma_f32 v[76:77], v[178:179], v[94:95], v[76:77]
	v_pk_mul_f32 v[94:95], v[156:157], v[190:191] op_sel_hi:[1,0]
	v_pk_fma_f32 v[74:75], v[100:101], v[98:99], v[74:75]
	v_pk_mul_f32 v[98:99], v[116:117], v[190:191] op_sel_hi:[1,0]
	v_pk_fma_f32 v[92:93], v[152:153], v[110:111], v[92:93]
	v_pk_fma_f32 v[90:91], v[154:155], v[126:127], v[90:91]
	v_pk_mul_f32 v[110:111], v[118:119], v[192:193] op_sel_hi:[1,0]
	v_pk_mul_f32 v[102:103], v[102:103], v[192:193] op_sel_hi:[1,0]
	v_pk_fma_f32 v[72:73], v[182:183], v[94:95], v[72:73]
	v_pk_mul_f32 v[94:95], v[120:121], v[192:193] op_sel_hi:[1,0]
	v_pk_fma_f32 v[68:69], v[186:187], v[98:99], v[68:69]
	v_pk_mul_f32 v[98:99], v[124:125], v[192:193] op_sel_hi:[1,0]
	v_pk_fma_f32 v[84:85], v[154:155], v[110:111], v[84:85]
	v_pk_mul_f32 v[110:111], v[114:115], v[190:191] op_sel_hi:[1,0]
	v_pk_fma_f32 v[82:83], v[170:171], v[102:103], v[82:83]
	v_pk_mul_f32 v[102:103], v[112:113], v[190:191] op_sel_hi:[1,0]
	v_pk_fma_f32 v[70:71], v[182:183], v[94:95], v[70:71]
	v_pk_mul_f32 v[94:95], v[184:185], v[190:191] op_sel_hi:[1,0]
	v_pk_fma_f32 v[98:99], v[188:189], v[98:99], v[108:109]
	v_cvt_pk_bf16_f32 v90, v90, v91
	v_cvt_pk_bf16_f32 v91, v92, v93
	v_pk_fma_f32 v[86:87], v[170:171], v[110:111], v[86:87]
	v_pk_fma_f32 v[78:79], v[100:101], v[102:103], v[78:79]
	v_pk_fma_f32 v[94:95], v[188:189], v[94:95], v[106:107]
	v_pk_mul_f32 v[100:101], v[104:105], v[192:193] op_sel_hi:[1,0]
	v_cvt_pk_bf16_f32 v92, v98, v99
	v_and_b32_e32 v99, 0xffff0000, v91
	v_and_b32_e32 v98, 0xffff0000, v90
	v_pk_fma_f32 v[66:67], v[186:187], v[100:101], v[66:67]
	v_cvt_pk_bf16_f32 v84, v84, v85
	v_cvt_pk_bf16_f32 v85, v88, v89
	v_cvt_pk_bf16_f32 v80, v80, v81
	v_cvt_pk_bf16_f32 v81, v86, v87
	v_cvt_pk_bf16_f32 v88, v94, v95
	v_lshlrev_b32_e32 v95, 16, v91
	v_lshlrev_b32_e32 v94, 16, v90
	v_pk_mul_f32 v[100:101], v[98:99], v[98:99]
	v_cvt_pk_bf16_f32 v87, v82, v83
	v_cvt_pk_bf16_f32 v82, v72, v73
	v_cvt_pk_bf16_f32 v83, v78, v79
	v_pk_fma_f32 v[100:101], v[94:95], v[94:95], v[100:101]
	v_and_b32_e32 v111, 0xffff0000, v81
	v_and_b32_e32 v110, 0xffff0000, v80
	v_cvt_pk_bf16_f32 v86, v76, v77
	v_cvt_pk_bf16_f32 v79, v74, v75
	v_lshlrev_b32_e32 v76, 16, v82
	v_and_b32_e32 v77, 0xffff0000, v82
	v_lshlrev_b32_e32 v72, 16, v88
	v_pk_add_f32 v[100:101], v[100:101], v[100:101] op_sel_hi:[0,1]
	v_lshlrev_b32_e32 v109, 16, v81
	v_lshlrev_b32_e32 v108, 16, v80
	v_pk_mul_f32 v[112:113], v[110:111], v[110:111]
	v_lshlrev_b32_e32 v122, 16, v83
	v_cvt_pk_bf16_f32 v89, v68, v69
	v_pk_fma_f32 v[112:113], v[108:109], v[108:109], v[112:113]
	v_mul_f32_e32 v73, v76, v76
	v_mul_f32_e32 v121, v77, v77
	v_and_b32_e32 v123, 0xffff0000, v83
	v_mul_f32_e32 v100, v122, v122
	v_lshlrev_b32_e32 v142, 16, v79
	v_mov_b32_e32 v120, v72
	v_cvt_pk_bf16_f32 v78, v70, v71
	v_and_b32_e32 v55, 0xffff0000, v88
	v_lshlrev_b32_e32 v70, 16, v89
	v_and_b32_e32 v71, 0xffff0000, v89
	v_and_b32_e32 v105, 0xffff0000, v85
	v_and_b32_e32 v104, 0xffff0000, v84
	v_pk_add_f32 v[112:113], v[112:113], v[112:113] op_sel_hi:[0,1]
	v_and_b32_e32 v117, 0xffff0000, v87
	v_and_b32_e32 v116, 0xffff0000, v86
	v_pk_fma_f32 v[124:125], v[122:123], v[122:123], v[100:101] op_sel_hi:[1,1,0]
	v_and_b32_e32 v143, 0xffff0000, v79
	v_mul_f32_e32 v100, v142, v142
	v_pk_add_f32 v[120:121], v[72:73], v[120:121]
	v_lshlrev_b32_e32 v74, 16, v78
	v_and_b32_e32 v75, 0xffff0000, v78
	v_lshlrev_b32_e32 v68, 16, v92
	v_lshlrev_b32_e32 v103, 16, v85
	v_lshlrev_b32_e32 v102, 16, v84
	v_pk_mul_f32 v[106:107], v[104:105], v[104:105]
	v_lshlrev_b32_e32 v115, 16, v87
	v_lshlrev_b32_e32 v114, 16, v86
	v_pk_mul_f32 v[118:119], v[116:117], v[116:117]
	v_pk_fma_f32 v[152:153], v[142:143], v[142:143], v[100:101] op_sel_hi:[1,1,0]
	v_mul_f32_e32 v124, v55, v55
	v_mul_f32_e32 v100, v70, v70
	v_mul_f32_e32 v112, v71, v71
	v_mul_f32_e32 v154, v72, v72
	v_mov_b32_e32 v155, v121
	v_cvt_pk_bf16_f32 v93, v66, v67
	v_pk_fma_f32 v[106:107], v[102:103], v[102:103], v[106:107]
	v_pk_fma_f32 v[118:119], v[114:115], v[114:115], v[118:119]
	v_mul_f32_e32 v69, v74, v74
	v_mul_f32_e32 v127, v75, v75
	v_pk_add_f32 v[120:121], v[154:155], v[124:125]
	v_pk_add_f32 v[100:101], v[100:101], v[112:113]
	v_mov_b32_e32 v126, v68
	v_and_b32_e32 v151, 0xffff0000, v92
	v_lshlrev_b32_e32 v66, 16, v93
	v_and_b32_e32 v67, 0xffff0000, v93
	v_pk_add_f32 v[106:107], v[106:107], v[106:107] op_sel_hi:[0,1]
	v_pk_add_f32 v[118:119], v[118:119], v[118:119] op_sel_hi:[0,1]
	v_pk_add_f32 v[100:101], v[120:121], v[100:101]
	v_pk_add_f32 v[120:121], v[68:69], v[126:127]
	v_mul_f32_e32 v152, v151, v151
	v_mul_f32_e32 v106, v66, v66
	v_mul_f32_e32 v118, v67, v67
	v_mul_f32_e32 v112, v68, v68
	v_mov_b32_e32 v113, v121
	v_pk_add_f32 v[112:113], v[112:113], v[152:153]
	v_pk_add_f32 v[106:107], v[106:107], v[118:119]
	s_waitcnt vmcnt(3)
	v_pk_add_f32 v[24:25], v[24:25], 1.0 op_sel_hi:[1,0]
	v_pk_add_f32 v[106:107], v[112:113], v[106:107]
	v_mov_b32_e32 v113, v100
	v_mov_b32_e32 v112, v106
	v_mov_b32_e32 v100, v107
	v_pk_add_f32 v[100:101], v[112:113], v[100:101]
	v_mov_b32_e32 v240, v100
	v_mov_b32_e32 v241, v101
	s_nop 1
	v_add_f32_dpp v240, v240, v240 quad_perm:[1,0,3,2] row_mask:0xf bank_mask:0xf
	v_add_f32_dpp v241, v241, v241 quad_perm:[1,0,3,2] row_mask:0xf bank_mask:0xf
	s_nop 0
	v_add_f32_dpp v240, v240, v240 quad_perm:[2,3,0,1] row_mask:0xf bank_mask:0xf
	v_add_f32_dpp v241, v241, v241 quad_perm:[2,3,0,1] row_mask:0xf bank_mask:0xf
	s_nop 0
	v_add_f32_dpp v240, v240, v240 row_half_mirror row_mask:0xf bank_mask:0xf
	v_add_f32_dpp v241, v241, v241 row_half_mirror row_mask:0xf bank_mask:0xf
	s_nop 0
	v_add_f32_dpp v240, v240, v240 row_mirror row_mask:0xf bank_mask:0xf
	v_add_f32_dpp v241, v241, v241 row_mirror row_mask:0xf bank_mask:0xf
	v_mov_b32_e32 v242, v240
	v_mov_b32_e32 v243, v241
	s_nop 1
	v_permlane16_swap_b32_e32 v240, v242
	v_permlane16_swap_b32_e32 v241, v243
	v_add_f32_e32 v240, v240, v242
	v_add_f32_e32 v241, v241, v243
	v_mov_b32_e32 v242, v240
	v_mov_b32_e32 v243, v241
	s_nop 1
	v_permlane32_swap_b32_e32 v240, v242
	v_permlane32_swap_b32_e32 v241, v243
	v_add_f32_e32 v240, v240, v242
	v_add_f32_e32 v241, v241, v243
	v_pk_add_f32 v[26:27], v[26:27], 1.0 op_sel_hi:[1,0]
	v_pk_mul_f32 v[24:25], v[20:21], v[24:25]
	v_pk_mul_f32 v[26:27], v[22:23], v[26:27]
	v_pk_mul_f32 v[96:97], v[30:31], v[96:97]
	v_pk_mul_f32 v[0:1], v[28:29], v[0:1]
	global_load_dwordx4 v[28:31], v[64:65], off offset:1024
	s_waitcnt vmcnt(3)
	v_pk_add_f32 v[14:15], v[14:15], 1.0 op_sel_hi:[1,0]
	v_pk_add_f32 v[12:13], v[12:13], 1.0 op_sel_hi:[1,0]
	s_waitcnt vmcnt(2)
	v_pk_mul_f32 v[34:35], v[34:35], v[14:15]
	v_pk_mul_f32 v[32:33], v[32:33], v[12:13]
	s_waitcnt vmcnt(1)
	v_pk_mul_f32 v[10:11], v[18:19], v[10:11]
	v_pk_add_f32 v[8:9], v[8:9], 1.0 op_sel_hi:[1,0]
	global_load_dwordx4 v[12:15], v[64:65], off offset:2048
	global_load_dwordx4 v[20:23], v[64:65], off offset:3072
	v_pk_mul_f32 v[8:9], v[16:17], v[8:9]
	global_store_dwordx2 v[62:63], v[90:91], off offset:2048
	global_store_dwordx2 v[60:61], v[84:85], off offset:2048
	global_store_dwordx2 v[62:63], v[80:81], off offset:2560
	global_store_dwordx2 v[60:61], v[86:87], off offset:2560
	global_store_dwordx2 v[62:63], v[82:83], off offset:3072
	global_store_dwordx2 v[60:61], v[78:79], off offset:3072
	global_store_dwordx2 v[62:63], v[88:89], off offset:3584
	v_mov_b32_e32 v62, v102
	v_mov_b32_e32 v63, v104
	v_mov_b32_e32 v104, v103
	global_store_dwordx2 v[60:61], v[92:93], off offset:3584
	v_mov_b32_e32 v73, v55
	v_mov_b32_e32 v69, v151
	v_mov_b32_e32 v16, v240
	v_mov_b32_e32 v17, v241
	s_nop 0
	v_pk_fma_f32 v[2:3], v[16:17], s[6:7], v[2:3] op_sel_hi:[1,0,0]
	v_mov_b32_e32 v18, v94
	v_mul_f32_e32 v16, 0x4b800000, v3
	v_cmp_gt_f32_e32 vcc, s0, v3
	v_cmp_gt_f32_e64 s[4:5], s0, v2
	v_mov_b32_e32 v19, v98
	v_cndmask_b32_e32 v3, v3, v16, vcc
	v_mul_f32_e32 v16, 0x4b800000, v2
	v_rsq_f32_e32 v3, v3
	v_cndmask_b32_e64 v2, v2, v16, s[4:5]
	v_rsq_f32_e32 v16, v2
	v_mov_b32_e32 v98, v95
	v_mul_f32_e32 v2, 0x45800000, v3
	v_cndmask_b32_e32 v2, v3, v2, vcc
	v_mul_f32_e32 v3, 0x45800000, v16
	v_cndmask_b32_e64 v16, v16, v3, s[4:5]
	v_pk_mul_f32 v[18:19], v[2:3], v[18:19] op_sel_hi:[0,1]
	v_pk_mul_f32 v[60:61], v[2:3], v[98:99] op_sel_hi:[0,1]
	v_pk_mul_f32 v[62:63], v[16:17], v[62:63] op_sel_hi:[0,1]
	v_pk_mul_f32 v[64:65], v[16:17], v[104:105] op_sel_hi:[0,1]
	v_pk_fma_f32 v[60:61], v[96:97], v[60:61], v[6:7]
	v_pk_fma_f32 v[18:19], v[0:1], v[18:19], v[4:5]
	v_pk_fma_f32 v[6:7], v[96:97], v[64:65], v[6:7]
	v_pk_fma_f32 v[0:1], v[0:1], v[62:63], v[4:5]
	s_mov_b32 s0, 0x5280000
	v_cvt_pk_bf16_f32 v0, v0, v1
	v_cvt_pk_bf16_f32 v1, v6, v7
	v_add_co_u32_e32 v6, vcc, s0, v58
	v_cvt_pk_bf16_f32 v4, v18, v19
	v_cvt_pk_bf16_f32 v5, v60, v61
	v_addc_co_u32_e32 v7, vcc, 0, v59, vcc
	global_store_dwordx2 v[6:7], v[4:5], off
	v_add_co_u32_e32 v4, vcc, s0, v56
	v_mov_b32_e32 v56, v114
	s_nop 0
	v_addc_co_u32_e32 v5, vcc, 0, v57, vcc
	global_store_dwordx2 v[4:5], v[0:1], off
	v_mov_b32_e32 v0, v108
	v_mov_b32_e32 v1, v110
	v_mov_b32_e32 v110, v109
	v_mov_b32_e32 v57, v116
	v_mov_b32_e32 v116, v115
	v_pk_mul_f32 v[0:1], v[2:3], v[0:1] op_sel_hi:[0,1]
	v_pk_mul_f32 v[18:19], v[2:3], v[110:111] op_sel_hi:[0,1]
	v_pk_mul_f32 v[56:57], v[16:17], v[56:57] op_sel_hi:[0,1]
	v_pk_mul_f32 v[58:59], v[16:17], v[116:117] op_sel_hi:[0,1]
	s_waitcnt vmcnt(12)
	v_pk_fma_f32 v[18:19], v[26:27], v[18:19], v[30:31]
	v_pk_fma_f32 v[0:1], v[24:25], v[0:1], v[28:29]
	v_pk_fma_f32 v[26:27], v[26:27], v[58:59], v[30:31]
	v_pk_fma_f32 v[24:25], v[24:25], v[56:57], v[28:29]
	v_cvt_pk_bf16_f32 v0, v0, v1
	v_cvt_pk_bf16_f32 v1, v18, v19
	v_cvt_pk_bf16_f32 v18, v24, v25
	v_cvt_pk_bf16_f32 v19, v26, v27
	global_store_dwordx2 v[6:7], v[0:1], off offset:512
	global_store_dwordx2 v[4:5], v[18:19], off offset:512
	v_pk_mul_f32 v[0:1], v[76:77], v[2:3] op_sel_hi:[1,0]
	v_pk_mul_f32 v[18:19], v[122:123], v[2:3] op_sel_hi:[1,0]
	s_waitcnt vmcnt(13)
	v_pk_fma_f32 v[0:1], v[32:33], v[0:1], v[12:13]
	v_pk_fma_f32 v[18:19], v[34:35], v[18:19], v[14:15]
	v_pk_mul_f32 v[24:25], v[74:75], v[16:17] op_sel_hi:[1,0]
	v_pk_mul_f32 v[26:27], v[142:143], v[16:17] op_sel_hi:[1,0]
	v_pk_fma_f32 v[12:13], v[32:33], v[24:25], v[12:13]
	v_pk_fma_f32 v[14:15], v[34:35], v[26:27], v[14:15]
	v_cvt_pk_bf16_f32 v0, v0, v1
	v_cvt_pk_bf16_f32 v1, v18, v19
	s_mov_b64 s[0:1], 0x800000
	v_cvt_pk_bf16_f32 v12, v12, v13
	v_cvt_pk_bf16_f32 v13, v14, v15
	global_store_dwordx2 v[6:7], v[0:1], off offset:1024
	global_store_dwordx2 v[4:5], v[12:13], off offset:1024
	v_pk_mul_f32 v[0:1], v[72:73], v[2:3] op_sel_hi:[1,0]
	v_pk_mul_f32 v[2:3], v[70:71], v[2:3] op_sel_hi:[1,0]
	v_lshl_add_u64 v[46:47], v[46:47], 0, s[0:1]
	v_lshl_add_u64 v[50:51], v[50:51], 0, s[0:1]
	s_mov_b32 s0, 0x8fff
	s_waitcnt vmcnt(14)
	v_pk_fma_f32 v[2:3], v[10:11], v[2:3], v[22:23]
	v_pk_fma_f32 v[0:1], v[8:9], v[0:1], v[20:21]
	v_pk_mul_f32 v[12:13], v[68:69], v[16:17] op_sel_hi:[1,0]
	v_pk_mul_f32 v[14:15], v[66:67], v[16:17] op_sel_hi:[1,0]
	s_mov_b64 s[4:5], 0x1000000
	v_cmp_lt_i32_e32 vcc, s0, v150
	v_pk_fma_f32 v[10:11], v[10:11], v[14:15], v[22:23]
	v_pk_fma_f32 v[8:9], v[8:9], v[12:13], v[20:21]
	v_cvt_pk_bf16_f32 v0, v0, v1
	v_cvt_pk_bf16_f32 v1, v2, v3
	v_lshl_add_u64 v[48:49], v[48:49], 0, s[4:5]
	s_or_b64 s[8:9], vcc, s[8:9]
	v_lshl_add_u64 v[52:53], v[52:53], 0, s[4:5]
	v_cvt_pk_bf16_f32 v2, v8, v9
	v_cvt_pk_bf16_f32 v3, v10, v11
	global_store_dwordx2 v[6:7], v[0:1], off offset:1536
	global_store_dwordx2 v[4:5], v[2:3], off offset:1536
	s_andn2_b64 exec, exec, s[8:9]
	s_cbranch_execz .LBB0_1376

.LBB0_1596:
	s_or_b64 exec, exec, s[0:1]
	v_add_u32_e32 v8, 0x6000, v28
	v_ashrrev_i32_e32 v8, 12, v8
	v_add_u32_e32 v8, 1, v8
	v_cmp_lt_i32_e32 vcc, s20, v113
	s_waitcnt vmcnt(14)
	v_lshlrev_b32_e32 v60, 16, v0
	v_and_b32_e32 v61, 0xffff0000, v0
	v_cndmask_b32_e32 v0, 0, v8, vcc
	v_lshlrev_b32_e32 v66, 16, v1
	v_and_b32_e32 v67, 0xffff0000, v1
	v_mul_hi_i32_i24_e32 v1, 0x9000, v0
	v_mul_i32_i24_e32 v0, 0x9000, v0
	v_lshl_add_u64 v[0:1], s[6:7], 0, v[0:1]
	v_mov_b32_e32 v47, v29
	v_lshl_add_u64 v[0:1], v[0:1], 0, v[46:47]
	v_add_co_u32_e32 v114, vcc, s11, v0
	v_lshlrev_b32_e32 v70, 16, v4
	v_and_b32_e32 v71, 0xffff0000, v4
	v_lshlrev_b32_e32 v72, 16, v5
	v_and_b32_e32 v73, 0xffff0000, v5
	s_waitcnt vmcnt(11)
	v_lshlrev_b32_e32 v64, 16, v6
	v_and_b32_e32 v65, 0xffff0000, v6
	v_lshlrev_b32_e32 v68, 16, v7
	v_and_b32_e32 v69, 0xffff0000, v7
	s_waitcnt vmcnt(10)
	v_lshlrev_b32_e32 v58, 16, v2
	v_and_b32_e32 v59, 0xffff0000, v2
	v_lshlrev_b32_e32 v62, 16, v3
	v_and_b32_e32 v63, 0xffff0000, v3
	v_lshl_add_u64 v[76:77], v[0:1], 0, s[8:9]
	v_addc_co_u32_e32 v115, vcc, 0, v1, vcc
	global_load_dwordx4 v[20:23], v[36:37], off
	global_load_dwordx4 v[0:3], v[36:37], off offset:1024
	global_load_dwordx4 v[4:7], v[76:77], off offset:1024
	global_load_dwordx4 v[8:11], v[76:77], off offset:2048
	global_load_dwordx4 v[12:15], v[36:37], off offset:2048
	global_load_dwordx4 v[24:27], v[114:115], off
	global_load_dwordx4 v[16:19], v[76:77], off offset:3072
	s_waitcnt vmcnt(14)
	v_lshlrev_b32_e32 v76, 16, v84
	v_and_b32_e32 v77, 0xffff0000, v84
	s_waitcnt vmcnt(13)
	v_lshlrev_b32_e32 v114, 16, v86
	v_and_b32_e32 v115, 0xffff0000, v86
	v_lshlrev_b32_e32 v84, 16, v85
	v_and_b32_e32 v85, 0xffff0000, v85
	v_lshlrev_b32_e32 v86, 16, v87
	v_and_b32_e32 v87, 0xffff0000, v87
	v_pk_add_f32 v[76:77], v[76:77], v[114:115]
	v_pk_add_f32 v[84:85], v[84:85], v[86:87]
	v_lshlrev_b32_e32 v86, 16, v90
	v_and_b32_e32 v87, 0xffff0000, v90
	v_lshlrev_b32_e32 v114, 16, v104
	v_and_b32_e32 v115, 0xffff0000, v104
	v_pk_add_f32 v[86:87], v[86:87], v[114:115]
	v_lshlrev_b32_e32 v90, 16, v91
	v_and_b32_e32 v91, 0xffff0000, v91
	v_lshlrev_b32_e32 v104, 16, v105
	v_and_b32_e32 v105, 0xffff0000, v105
	v_mov_b32_e32 v114, v77
	v_mov_b32_e32 v115, v85
	v_pk_add_f32 v[90:91], v[90:91], v[104:105]
	v_mov_b32_e32 v104, v76
	v_mov_b32_e32 v105, v84
	v_pk_mul_f32 v[114:115], v[114:115], v[114:115]
	v_mov_b32_e32 v116, v87
	v_pk_fma_f32 v[104:105], v[104:105], v[104:105], v[114:115]
	v_mov_b32_e32 v117, v91
	v_pk_add_f32 v[114:115], v[104:105], v[104:105] op_sel:[0,1] op_sel_hi:[1,0]
	v_mov_b32_e32 v104, v86
	v_mov_b32_e32 v105, v90
	v_pk_mul_f32 v[116:117], v[116:117], v[116:117]
	s_waitcnt vmcnt(11)
	v_lshlrev_b32_e32 v118, 16, v88
	v_pk_fma_f32 v[116:117], v[104:105], v[104:105], v[116:117]
	v_lshlrev_b32_e32 v104, 16, v102
	v_and_b32_e32 v105, 0xffff0000, v102
	v_and_b32_e32 v119, 0xffff0000, v88
	v_lshlrev_b32_e32 v102, 16, v103
	v_and_b32_e32 v103, 0xffff0000, v103
	v_lshlrev_b32_e32 v88, 16, v89
	v_and_b32_e32 v89, 0xffff0000, v89
	v_pk_add_f32 v[104:105], v[104:105], v[118:119]
	v_pk_add_f32 v[88:89], v[102:103], v[88:89]
	v_lshlrev_b32_e32 v102, 16, v94
	v_and_b32_e32 v103, 0xffff0000, v94
	v_lshlrev_b32_e32 v118, 16, v106
	v_and_b32_e32 v119, 0xffff0000, v106
	v_pk_add_f32 v[102:103], v[102:103], v[118:119]
	v_lshlrev_b32_e32 v94, 16, v95
	v_and_b32_e32 v95, 0xffff0000, v95
	v_lshlrev_b32_e32 v106, 16, v107
	v_and_b32_e32 v107, 0xffff0000, v107
	v_mov_b32_e32 v118, v105
	v_mov_b32_e32 v119, v89
	v_pk_add_f32 v[94:95], v[94:95], v[106:107]
	v_mov_b32_e32 v106, v104
	v_mov_b32_e32 v107, v88
	v_pk_mul_f32 v[118:119], v[118:119], v[118:119]
	v_mov_b32_e32 v120, v103
	v_pk_fma_f32 v[106:107], v[106:107], v[106:107], v[118:119]
	v_mov_b32_e32 v121, v95
	v_pk_add_f32 v[118:119], v[106:107], v[106:107] op_sel:[0,1] op_sel_hi:[1,0]
	v_mov_b32_e32 v106, v102
	v_mov_b32_e32 v107, v94
	v_pk_mul_f32 v[120:121], v[120:121], v[120:121]
	s_waitcnt vmcnt(9)
	v_lshlrev_b32_e32 v122, 16, v78
	v_pk_fma_f32 v[120:121], v[106:107], v[106:107], v[120:121]
	v_lshlrev_b32_e32 v106, 16, v96
	v_and_b32_e32 v107, 0xffff0000, v96
	v_and_b32_e32 v123, 0xffff0000, v78
	v_lshlrev_b32_e32 v96, 16, v97
	v_and_b32_e32 v97, 0xffff0000, v97
	v_lshlrev_b32_e32 v78, 16, v79
	v_and_b32_e32 v79, 0xffff0000, v79
	v_pk_add_f32 v[106:107], v[106:107], v[122:123]
	v_pk_add_f32 v[96:97], v[96:97], v[78:79]
	v_lshlrev_b32_e32 v78, 16, v92
	v_and_b32_e32 v79, 0xffff0000, v92
	v_lshlrev_b32_e32 v122, 16, v100
	v_and_b32_e32 v123, 0xffff0000, v100
	v_pk_add_f32 v[122:123], v[78:79], v[122:123]
	v_lshlrev_b32_e32 v78, 16, v93
	v_and_b32_e32 v79, 0xffff0000, v93
	v_lshlrev_b32_e32 v92, 16, v101
	v_and_b32_e32 v93, 0xffff0000, v101
	v_pk_add_f32 v[92:93], v[78:79], v[92:93]
	v_mul_f32_e32 v78, v107, v107
	v_pk_fma_f32 v[100:101], v[106:107], v[106:107], v[78:79] op_sel_hi:[1,1,0]
	s_waitcnt vmcnt(8)
	v_lshlrev_b32_e32 v78, 16, v98
	v_and_b32_e32 v79, 0xffff0000, v98
	s_waitcnt vmcnt(7)
	v_lshlrev_b32_e32 v124, 16, v80
	v_and_b32_e32 v125, 0xffff0000, v80
	v_pk_add_f32 v[124:125], v[78:79], v[124:125]
	v_lshlrev_b32_e32 v78, 16, v99
	v_and_b32_e32 v79, 0xffff0000, v99
	v_lshlrev_b32_e32 v80, 16, v81
	v_and_b32_e32 v81, 0xffff0000, v81
	v_pk_add_f32 v[98:99], v[78:79], v[80:81]
	global_load_dwordx4 v[78:81], v[36:37], off offset:3072
	v_lshlrev_b32_e32 v126, 16, v74
	v_and_b32_e32 v127, 0xffff0000, v74
	v_lshlrev_b32_e32 v128, 16, v82
	v_and_b32_e32 v129, 0xffff0000, v82
	v_lshlrev_b32_e32 v74, 16, v75
	v_and_b32_e32 v75, 0xffff0000, v75
	v_lshlrev_b32_e32 v82, 16, v83
	v_and_b32_e32 v83, 0xffff0000, v83
	v_pk_add_f32 v[126:127], v[126:127], v[128:129]
	v_mul_f32_e32 v128, v97, v97
	v_pk_add_f32 v[74:75], v[74:75], v[82:83]
	v_pk_mul_f32 v[82:83], v[124:125], v[124:125]
	v_pk_fma_f32 v[128:129], v[96:97], v[96:97], v[128:129] op_sel_hi:[1,1,0]
	v_mov_b32_e32 v115, v82
	v_mov_b32_e32 v119, v83
	v_pk_mul_f32 v[82:83], v[98:99], v[98:99]
	v_pk_add_f32 v[114:115], v[114:115], v[118:119]
	v_mov_b32_e32 v101, v82
	v_mov_b32_e32 v129, v83
	v_pk_add_f32 v[100:101], v[100:101], v[128:129]
	v_pk_add_f32 v[82:83], v[116:117], v[116:117] op_sel:[0,1] op_sel_hi:[1,0]
	v_pk_add_f32 v[116:117], v[120:121], v[120:121] op_sel:[0,1] op_sel_hi:[1,0]
	v_pk_add_f32 v[100:101], v[114:115], v[100:101]
	v_pk_mul_f32 v[114:115], v[126:127], v[126:127]
	v_mul_f32_e32 v118, v123, v123
	v_mov_b32_e32 v83, v114
	v_mov_b32_e32 v117, v115
	v_mul_f32_e32 v114, v93, v93
	v_pk_fma_f32 v[118:119], v[122:123], v[122:123], v[118:119] op_sel_hi:[1,1,0]
	v_pk_fma_f32 v[114:115], v[92:93], v[92:93], v[114:115] op_sel_hi:[1,1,0]
	v_pk_add_f32 v[82:83], v[82:83], v[116:117]
	v_pk_mul_f32 v[116:117], v[74:75], v[74:75]
	s_waitcnt vmcnt(2)
	v_pk_mul_f32 v[22:23], v[26:27], v[22:23]
	v_mov_b32_e32 v119, v116
	v_mov_b32_e32 v115, v117
	v_pk_add_f32 v[114:115], v[118:119], v[114:115]
	v_pk_mul_f32 v[120:121], v[4:5], v[0:1]
	v_pk_add_f32 v[82:83], v[82:83], v[114:115]
	v_mov_b32_e32 v115, v100
	v_mov_b32_e32 v114, v82
	v_mov_b32_e32 v100, v83
	v_pk_add_f32 v[82:83], v[114:115], v[100:101]
	v_mov_b32_e32 v240, v82
	v_mov_b32_e32 v241, v83
	s_nop 1
	v_add_f32_dpp v240, v240, v240 quad_perm:[1,0,3,2] row_mask:0xf bank_mask:0xf
	v_add_f32_dpp v241, v241, v241 quad_perm:[1,0,3,2] row_mask:0xf bank_mask:0xf
	s_nop 0
	v_add_f32_dpp v240, v240, v240 quad_perm:[2,3,0,1] row_mask:0xf bank_mask:0xf
	v_add_f32_dpp v241, v241, v241 quad_perm:[2,3,0,1] row_mask:0xf bank_mask:0xf
	s_nop 0
	v_add_f32_dpp v240, v240, v240 row_half_mirror row_mask:0xf bank_mask:0xf
	v_add_f32_dpp v241, v241, v241 row_half_mirror row_mask:0xf bank_mask:0xf
	s_nop 0
	v_add_f32_dpp v240, v240, v240 row_mirror row_mask:0xf bank_mask:0xf
	v_add_f32_dpp v241, v241, v241 row_mirror row_mask:0xf bank_mask:0xf
	v_mov_b32_e32 v242, v240
	v_mov_b32_e32 v243, v241
	s_nop 1
	v_permlane16_swap_b32_e32 v240, v242
	v_permlane16_swap_b32_e32 v241, v243
	v_add_f32_e32 v240, v240, v242
	v_add_f32_e32 v241, v241, v243
	v_mov_b32_e32 v242, v240
	v_mov_b32_e32 v243, v241
	s_nop 1
	v_permlane32_swap_b32_e32 v240, v242
	v_permlane32_swap_b32_e32 v241, v243
	v_add_f32_e32 v240, v240, v242
	v_add_f32_e32 v241, v241, v243
	v_pk_mul_f32 v[118:119], v[6:7], v[2:3]
	v_lshlrev_b32_e32 v114, 16, v56
	v_and_b32_e32 v115, 0xffff0000, v56
	v_lshlrev_b32_e32 v56, 16, v57
	v_and_b32_e32 v57, 0xffff0000, v57
	v_lshlrev_b32_e32 v116, 16, v54
	v_and_b32_e32 v117, 0xffff0000, v54
	v_lshlrev_b32_e32 v54, 16, v55
	v_and_b32_e32 v55, 0xffff0000, v55
	v_pk_mul_f32 v[20:21], v[24:25], v[20:21]
	v_lshlrev_b32_e32 v24, 16, v52
	v_and_b32_e32 v25, 0xffff0000, v52
	v_lshlrev_b32_e32 v52, 16, v53
	v_and_b32_e32 v53, 0xffff0000, v53
	v_lshlrev_b32_e32 v100, 16, v50
	v_and_b32_e32 v101, 0xffff0000, v50
	v_lshlrev_b32_e32 v50, 16, v51
	v_and_b32_e32 v51, 0xffff0000, v51
	v_add_u32_e32 v28, 0x1000, v28
	v_lshl_add_u64 v[38:39], v[38:39], 0, s[12:13]
	v_pk_mul_f32 v[26:27], v[10:11], v[14:15]
	s_waitcnt vmcnt(0)
	v_pk_mul_f32 v[80:81], v[18:19], v[80:81]
	v_pk_mul_f32 v[78:79], v[16:17], v[78:79]
	v_pk_mul_f32 v[82:83], v[8:9], v[12:13]
	v_mov_b32_e32 v0, v240
	v_mov_b32_e32 v1, v241
	v_lshl_add_u64 v[44:45], v[44:45], 0, s[12:13]
	v_pk_fma_f32 v[0:1], v[0:1], s[10:11], v[48:49] op_sel_hi:[1,0,0]
	s_nop 0
	v_mul_f32_e32 v2, 0x4b800000, v1
	v_cmp_gt_f32_e32 vcc, s21, v1
	v_cmp_gt_f32_e64 s[0:1], s21, v0
	s_nop 0
	v_cndmask_b32_e32 v1, v1, v2, vcc
	v_rsq_f32_e32 v1, v1
	v_mul_f32_e32 v2, 0x4b800000, v0
	v_cndmask_b32_e64 v0, v0, v2, s[0:1]
	v_rsq_f32_e32 v0, v0
	v_mul_f32_e32 v2, 0x45800000, v1
	v_cndmask_b32_e32 v1, v1, v2, vcc
	v_mul_f32_e32 v128, 0.5, v1
	v_mul_f32_e32 v1, 0x45800000, v0
	v_cndmask_b32_e64 v0, v0, v1, s[0:1]
	v_mul_f32_e32 v130, 0.5, v0
	v_pk_mul_f32 v[2:3], v[84:85], v[128:129] op_sel_hi:[1,0]
	v_pk_mul_f32 v[6:7], v[90:91], v[130:131] op_sel_hi:[1,0]
	v_pk_fma_f32 v[2:3], v[22:23], v[2:3], v[72:73]
	v_pk_fma_f32 v[6:7], v[22:23], v[6:7], v[68:69]
	v_pk_mul_f32 v[18:19], v[96:97], v[128:129] op_sel_hi:[1,0]
	v_pk_mul_f32 v[22:23], v[92:93], v[130:131] op_sel_hi:[1,0]
	v_pk_fma_f32 v[18:19], v[26:27], v[18:19], v[56:57]
	v_pk_fma_f32 v[22:23], v[26:27], v[22:23], v[54:55]
	v_pk_mul_f32 v[54:55], v[124:125], v[128:129] op_sel_hi:[1,0]
	v_pk_mul_f32 v[26:27], v[98:99], v[128:129] op_sel_hi:[1,0]
	v_pk_mul_f32 v[0:1], v[76:77], v[128:129] op_sel_hi:[1,0]
	v_pk_mul_f32 v[4:5], v[86:87], v[130:131] op_sel_hi:[1,0]
	v_pk_fma_f32 v[26:27], v[80:81], v[26:27], v[52:53]
	v_pk_fma_f32 v[24:25], v[78:79], v[54:55], v[24:25]
	v_pk_mul_f32 v[54:55], v[126:127], v[130:131] op_sel_hi:[1,0]
	v_pk_mul_f32 v[52:53], v[74:75], v[130:131] op_sel_hi:[1,0]
	v_cmp_lt_i32_e32 vcc, s22, v113
	v_pk_fma_f32 v[0:1], v[20:21], v[0:1], v[70:71]
	v_pk_fma_f32 v[4:5], v[20:21], v[4:5], v[64:65]
	v_pk_mul_f32 v[8:9], v[104:105], v[128:129] op_sel_hi:[1,0]
	v_pk_mul_f32 v[10:11], v[88:89], v[128:129] op_sel_hi:[1,0]
	v_pk_mul_f32 v[12:13], v[102:103], v[130:131] op_sel_hi:[1,0]
	v_pk_mul_f32 v[14:15], v[94:95], v[130:131] op_sel_hi:[1,0]
	v_pk_mul_f32 v[16:17], v[106:107], v[128:129] op_sel_hi:[1,0]
	v_pk_mul_f32 v[20:21], v[122:123], v[130:131] op_sel_hi:[1,0]
	v_pk_fma_f32 v[52:53], v[80:81], v[52:53], v[50:51]
	v_pk_fma_f32 v[50:51], v[78:79], v[54:55], v[100:101]
	v_lshl_add_u64 v[54:55], v[40:41], 0, v[34:35]
	v_lshl_add_u64 v[56:57], v[42:43], 0, v[34:35]
	v_lshl_add_u64 v[40:41], v[40:41], 0, s[14:15]
	v_lshl_add_u64 v[42:43], v[42:43], 0, s[14:15]
	s_or_b64 s[4:5], vcc, s[4:5]
	v_pk_fma_f32 v[10:11], v[118:119], v[10:11], v[66:67]
	v_pk_fma_f32 v[8:9], v[120:121], v[8:9], v[60:61]
	v_pk_fma_f32 v[14:15], v[118:119], v[14:15], v[62:63]
	v_pk_fma_f32 v[12:13], v[120:121], v[12:13], v[58:59]
	v_pk_fma_f32 v[16:17], v[82:83], v[16:17], v[114:115]
	v_pk_fma_f32 v[20:21], v[82:83], v[20:21], v[116:117]
	global_store_dwordx4 v[54:55], v[0:3], off
	global_store_dwordx4 v[56:57], v[4:7], off
	global_store_dwordx4 v[54:55], v[8:11], off offset:1024
	global_store_dwordx4 v[56:57], v[12:15], off offset:1024
	global_store_dwordx4 v[54:55], v[16:19], off offset:2048
	global_store_dwordx4 v[56:57], v[20:23], off offset:2048
	global_store_dwordx4 v[54:55], v[24:27], off offset:3072
	global_store_dwordx4 v[56:57], v[50:53], off offset:3072
	s_andn2_b64 exec, exec, s[4:5]
	s_cbranch_execz .LBB0_1613
